# up-GEMM ConvGLU epilogue: all eight row-rsqrt scalars loaded with the first batch (was 6 serial waits, some behind stores)
# baseline (speedup 1.0000x reference)
.LBB0_1549:
	s_cmp_lt_i32 s60, 64
	s_movk_i32 s27, 0x2c00
	s_cselect_b32 s27, s27, 0x5800
	s_cmp_gt_i32 s60, 31
	s_cselect_b32 s27, s27, 0
	v_lshl_or_b32 v188, s84, 7, v223
	s_lshl_b32 s27, s27, 2
	v_lshl_or_b32 v186, s84, 8, v223
	s_add_u32 s36, s66, s27
	v_ashrrev_i32_e32 v189, 31, v188
	v_lshl_add_u32 v190, s60, 8, v207
	s_addc_u32 s37, s67, 0
	v_ashrrev_i32_e32 v187, 31, v186
	v_lshlrev_b64 v[44:45], 2, v[188:189]
	v_ashrrev_i32_e32 v191, 31, v190
	v_lshl_add_u64 v[48:49], v[186:187], 2, s[36:37]
	v_lshl_add_u64 v[52:53], s[52:53], 0, v[44:45]
	v_lshl_add_u64 v[54:55], s[80:81], 0, v[44:45]
	v_lshl_add_u64 v[56:57], s[82:83], 0, v[44:45]
	v_lshl_add_u64 v[76:77], s[54:55], 0, v[44:45]
	v_lshl_add_u64 v[192:193], v[190:191], 2, s[64:65]
	global_load_dwordx4 v[84:87], v[48:49], off offset:16
	global_load_dwordx4 v[88:91], v[48:49], off
	global_load_dwordx4 v[44:47], v[48:49], off offset:528
	global_load_dwordx4 v[64:67], v[48:49], off offset:512
	s_nop 0
	global_load_dwordx4 v[48:51], v[52:53], off offset:16
	global_load_dwordx4 v[68:71], v[52:53], off
	global_load_dwordx4 v[60:63], v[54:55], off offset:16
	global_load_dwordx4 v[80:83], v[54:55], off
	s_nop 0
	global_load_dwordx4 v[52:55], v[56:57], off offset:16
	global_load_dwordx4 v[72:75], v[56:57], off
	s_nop 0
	global_load_dwordx4 v[56:59], v[76:77], off offset:16
	s_nop 0
	global_load_dwordx4 v[76:79], v[76:77], off
	v_or_b32_e32 v194, 16, v190
	global_load_dword v206, v[192:193], off
	global_load_dword v225, v[192:193], off offset:64
	global_load_dword v226, v[192:193], off offset:128
	global_load_dword v227, v[192:193], off offset:192
	global_load_dword v228, v[192:193], off offset:512
	global_load_dword v229, v[192:193], off offset:576
	global_load_dword v230, v[192:193], off offset:640
	global_load_dword v231, v[192:193], off offset:704
	v_ashrrev_i32_e32 v195, 31, v194
	v_mov_b32_e32 v212, v209
	v_mov_b32_e32 v213, v209
	s_mov_b32 s36, 0xbf3a00e3
	s_waitcnt vmcnt(0)
	v_pk_fma_f32 v[200:201], v[168:169], v[206:207], v[84:85] op_sel_hi:[1,0,1]
	v_lshl_add_u64 v[168:169], v[194:195], 2, s[64:65]
	s_nop 1
	v_mov_b32_e32 v196, v225
	v_pk_fma_f32 v[202:203], v[174:175], v[206:207], v[90:91] op_sel_hi:[1,0,1]
	v_pk_fma_f32 v[204:205], v[172:173], v[206:207], v[88:89] op_sel_hi:[1,0,1]
	v_pk_mul_f32 v[214:215], v[82:83], v[202:203]
	v_pk_mul_f32 v[216:217], v[80:81], v[204:205]
	v_mov_b32_dpp v212, v204 row_shr:1 row_mask:0xf bank_mask:0xf
	v_mov_b32_dpp v213, v205 row_shr:1 row_mask:0xf bank_mask:0xf
	v_pk_fma_f32 v[212:213], v[68:69], v[212:213], v[216:217]
	v_pk_fma_f32 v[198:199], v[170:171], v[206:207], v[86:87] op_sel_hi:[1,0,1]
	v_mov_b64_e32 v[216:217], s[36:37]
	v_pk_fma_f32 v[154:155], v[154:155], v[206:207], v[46:47] op_sel_hi:[1,0,1]
	v_pk_fma_f32 v[152:153], v[152:153], v[206:207], v[44:45] op_sel_hi:[1,0,1]
	s_nop 1
	v_pk_fma_f32 v[174:175], v[164:165], v[196:197], v[88:89] op_sel_hi:[1,0,1]
	s_nop 1
	v_mov_b32_dpp v210, v174 row_ror:15 row_mask:0xf bank_mask:0xf bound_ctrl:1
	v_mov_b32_dpp v211, v175 row_ror:15 row_mask:0xf bank_mask:0xf bound_ctrl:1
	v_pk_fma_f32 v[172:173], v[166:167], v[196:197], v[90:91] op_sel_hi:[1,0,1]
	v_mov_b32_dpp v210, v204 row_shl:1 row_mask:0xf bank_mask:0xf
	v_mov_b32_dpp v211, v205 row_shl:1 row_mask:0xf bank_mask:0xf
	v_pk_fma_f32 v[210:211], v[72:73], v[210:211], v[212:213]
	v_mov_b32_e32 v212, v209
	v_mov_b32_e32 v213, v209
	v_or_b32_e32 v164, 32, v190
	v_pk_add_f32 v[220:221], v[76:77], v[210:211]
	v_mov_b32_dpp v210, v172 row_ror:15 row_mask:0xf bank_mask:0xf bound_ctrl:1
	v_mov_b32_dpp v212, v202 row_shr:1 row_mask:0xf bank_mask:0xf
	v_mov_b32_dpp v211, v173 row_ror:15 row_mask:0xf bank_mask:0xf bound_ctrl:1
	v_mov_b32_dpp v213, v203 row_shr:1 row_mask:0xf bank_mask:0xf
	v_ashrrev_i32_e32 v165, 31, v164
	v_mov_b32_dpp v210, v202 row_shl:1 row_mask:0xf bank_mask:0xf
	v_mov_b32_dpp v211, v203 row_shl:1 row_mask:0xf bank_mask:0xf
	v_pk_fma_f32 v[212:213], v[70:71], v[212:213], v[214:215]
	v_pk_fma_f32 v[170:171], v[160:161], v[196:197], v[84:85] op_sel_hi:[1,0,1]
	v_lshl_add_u64 v[160:161], v[164:165], 2, s[64:65]
	v_pk_fma_f32 v[210:211], v[74:75], v[210:211], v[212:213]
	s_nop 1
	v_mov_b32_e32 v166, v226
	v_or_b32_e32 v160, 48, v190
	v_pk_add_f32 v[218:219], v[78:79], v[210:211]
	v_and_b32_e32 v211, 0x7fffffff, v221
	v_and_b32_e32 v210, 0x7fffffff, v220
	v_ashrrev_i32_e32 v161, 31, v160
	v_pk_fma_f32 v[210:211], v[210:211], s[26:27], 1.0 op_sel_hi:[1,0,0]
	v_pk_fma_f32 v[168:169], v[162:163], v[196:197], v[86:87] op_sel_hi:[1,0,1]
	v_lshl_add_u64 v[162:163], v[160:161], 2, s[64:65]
	v_rcp_f32_e32 v210, v210
	v_rcp_f32_e32 v211, v211
	s_nop 1
	v_mov_b32_e32 v162, v227
	v_cmp_gt_f32_e32 vcc, 0, v220
	v_pk_mul_f32 v[214:215], v[60:61], v[200:201]
	v_pk_fma_f32 v[212:213], v[210:211], s[72:73], v[216:217] op_sel_hi:[1,0,0]
	s_nop 0
	v_pk_fma_f32 v[212:213], v[210:211], v[212:213], s[16:17] op_sel_hi:[1,1,0]
	s_nop 0
	v_pk_fma_f32 v[212:213], v[210:211], v[212:213], s[78:79] op_sel_hi:[1,1,0]
	s_nop 0
	v_pk_fma_f32 v[212:213], v[210:211], v[212:213], s[0:1] op_sel_hi:[1,1,0]
	s_nop 0
	v_pk_mul_f32 v[210:211], v[210:211], v[212:213]
	v_pk_mul_f32 v[212:213], v[220:221], v[220:221]
	s_nop 0
	v_pk_mul_f32 v[212:213], v[212:213], s[28:29] op_sel_hi:[1,0]
	s_nop 0
	v_exp_f32_e32 v212, v212
	v_exp_f32_e32 v213, v213
	s_nop 0
	v_pk_mul_f32 v[210:211], v[212:213], v[210:211]
	s_nop 0
	v_pk_mul_f32 v[212:213], v[220:221], v[210:211]
	v_pk_fma_f32 v[210:211], v[220:221], v[210:211], v[220:221] neg_lo:[1,0,0] neg_hi:[1,0,0]
	s_nop 0
	v_cndmask_b32_e32 v161, v210, v212, vcc
	v_cmp_gt_f32_e32 vcc, 0, v221
	v_and_b32_e32 v210, 0x7fffffff, v218
	v_pk_fma_f32 v[220:221], v[156:157], v[206:207], v[64:65] op_sel_hi:[1,0,1]
	v_cndmask_b32_e32 v163, v211, v213, vcc
	v_and_b32_e32 v211, 0x7fffffff, v219
	v_pk_fma_f32 v[210:211], v[210:211], s[26:27], 1.0 op_sel_hi:[1,0,0]
	v_cmp_gt_f32_e32 vcc, 0, v218
	v_rcp_f32_e32 v210, v210
	v_rcp_f32_e32 v211, v211
	v_mul_f32_e32 v156, v220, v161
	v_mul_f32_e32 v157, v221, v163
	v_cvt_pk_bf16_f32 v156, v156, v157
	v_pk_fma_f32 v[212:213], v[210:211], s[72:73], v[216:217] op_sel_hi:[1,0,0]
	s_nop 0
	v_pk_fma_f32 v[212:213], v[210:211], v[212:213], s[16:17] op_sel_hi:[1,1,0]
	s_nop 0
	v_pk_fma_f32 v[212:213], v[210:211], v[212:213], s[78:79] op_sel_hi:[1,1,0]
	s_nop 0
	v_pk_fma_f32 v[212:213], v[210:211], v[212:213], s[0:1] op_sel_hi:[1,1,0]
	s_nop 0
	v_pk_mul_f32 v[210:211], v[210:211], v[212:213]
	v_pk_mul_f32 v[212:213], v[218:219], v[218:219]
	s_nop 0
	v_pk_mul_f32 v[212:213], v[212:213], s[28:29] op_sel_hi:[1,0]
	s_nop 0
	v_exp_f32_e32 v212, v212
	v_exp_f32_e32 v213, v213
	s_nop 0
	v_pk_mul_f32 v[210:211], v[212:213], v[210:211]
	s_nop 0
	v_pk_mul_f32 v[212:213], v[218:219], v[210:211]
	v_pk_fma_f32 v[210:211], v[218:219], v[210:211], v[218:219] neg_lo:[1,0,0] neg_hi:[1,0,0]
	s_nop 0
	v_cndmask_b32_e32 v165, v210, v212, vcc
	v_cmp_gt_f32_e32 vcc, 0, v219
	v_pk_fma_f32 v[218:219], v[158:159], v[206:207], v[66:67] op_sel_hi:[1,0,1]
	v_mov_b32_e32 v210, v209
	v_cndmask_b32_e32 v167, v211, v213, vcc
	v_mul_f32_e32 v157, v218, v165
	v_mul_f32_e32 v158, v219, v167
	v_mov_b32_e32 v211, v209
	v_cvt_pk_bf16_f32 v157, v157, v158
	v_mov_b32_dpp v210, v200 row_shr:1 row_mask:0xf bank_mask:0xf
	v_mov_b32_dpp v158, v170 row_ror:15 row_mask:0xf bank_mask:0xf bound_ctrl:1
	v_mov_b32_dpp v159, v171 row_ror:15 row_mask:0xf bank_mask:0xf bound_ctrl:1
	v_mov_b32_dpp v211, v201 row_shr:1 row_mask:0xf bank_mask:0xf
	v_mov_b32_dpp v158, v200 row_shl:1 row_mask:0xf bank_mask:0xf
	v_mov_b32_dpp v159, v201 row_shl:1 row_mask:0xf bank_mask:0xf
	v_pk_fma_f32 v[210:211], v[48:49], v[210:211], v[214:215]
	v_mov_b32_e32 v214, v209
	v_mov_b32_e32 v215, v209
	v_pk_mul_f32 v[212:213], v[62:63], v[198:199]
	v_pk_fma_f32 v[158:159], v[52:53], v[158:159], v[210:211]
	v_mov_b32_dpp v210, v168 row_ror:15 row_mask:0xf bank_mask:0xf bound_ctrl:1
	v_mov_b32_dpp v214, v198 row_shr:1 row_mask:0xf bank_mask:0xf
	v_mov_b32_dpp v211, v169 row_ror:15 row_mask:0xf bank_mask:0xf bound_ctrl:1
	v_mov_b32_dpp v215, v199 row_shr:1 row_mask:0xf bank_mask:0xf
	v_pk_add_f32 v[158:159], v[56:57], v[158:159]
	v_mov_b32_dpp v210, v198 row_shl:1 row_mask:0xf bank_mask:0xf
	v_mov_b32_dpp v211, v199 row_shl:1 row_mask:0xf bank_mask:0xf
	v_pk_fma_f32 v[212:213], v[50:51], v[214:215], v[212:213]
	v_cmp_gt_f32_e32 vcc, 0, v158
	v_pk_fma_f32 v[210:211], v[54:55], v[210:211], v[212:213]
	v_and_b32_e32 v213, 0x7fffffff, v159
	v_and_b32_e32 v212, 0x7fffffff, v158
	v_pk_fma_f32 v[212:213], v[212:213], s[26:27], 1.0 op_sel_hi:[1,0,0]
	v_pk_add_f32 v[210:211], v[58:59], v[210:211]
	v_rcp_f32_e32 v212, v212
	v_rcp_f32_e32 v213, v213
	s_nop 0
	v_pk_fma_f32 v[214:215], v[212:213], s[72:73], v[216:217] op_sel_hi:[1,0,0]
	s_nop 0
	v_pk_fma_f32 v[214:215], v[212:213], v[214:215], s[16:17] op_sel_hi:[1,1,0]
	s_nop 0
	v_pk_fma_f32 v[214:215], v[212:213], v[214:215], s[78:79] op_sel_hi:[1,1,0]
	s_nop 0
	v_pk_fma_f32 v[214:215], v[212:213], v[214:215], s[0:1] op_sel_hi:[1,1,0]
	s_nop 0
	v_pk_mul_f32 v[212:213], v[212:213], v[214:215]
	v_pk_mul_f32 v[214:215], v[158:159], v[158:159]
	s_nop 0
	v_pk_mul_f32 v[214:215], v[214:215], s[28:29] op_sel_hi:[1,0]
	s_nop 0
	v_exp_f32_e32 v214, v214
	v_exp_f32_e32 v215, v215
	s_nop 0
	v_pk_mul_f32 v[212:213], v[214:215], v[212:213]
	s_nop 0
	v_pk_mul_f32 v[214:215], v[158:159], v[212:213]
	v_pk_fma_f32 v[212:213], v[158:159], v[212:213], v[158:159] neg_lo:[1,0,0] neg_hi:[1,0,0]
	v_and_b32_e32 v158, 0x7fffffff, v210
	v_cndmask_b32_e32 v161, v212, v214, vcc
	v_cmp_gt_f32_e32 vcc, 0, v159
	v_and_b32_e32 v159, 0x7fffffff, v211
	v_pk_fma_f32 v[158:159], v[158:159], s[26:27], 1.0 op_sel_hi:[1,0,0]
	v_cndmask_b32_e32 v163, v213, v215, vcc
	v_rcp_f32_e32 v158, v158
	v_rcp_f32_e32 v159, v159
	v_cmp_gt_f32_e32 vcc, 0, v210
	v_pk_fma_f32 v[212:213], v[158:159], s[72:73], v[216:217] op_sel_hi:[1,0,0]
	s_nop 0
	v_pk_fma_f32 v[212:213], v[158:159], v[212:213], s[16:17] op_sel_hi:[1,1,0]
	s_nop 0
	v_pk_fma_f32 v[212:213], v[158:159], v[212:213], s[78:79] op_sel_hi:[1,1,0]
	s_nop 0
	v_pk_fma_f32 v[212:213], v[158:159], v[212:213], s[0:1] op_sel_hi:[1,1,0]
	s_nop 0
	v_pk_mul_f32 v[158:159], v[158:159], v[212:213]
	v_pk_mul_f32 v[212:213], v[210:211], v[210:211]
	s_nop 0
	v_pk_mul_f32 v[212:213], v[212:213], s[28:29] op_sel_hi:[1,0]
	s_nop 0
	v_exp_f32_e32 v212, v212
	v_exp_f32_e32 v213, v213
	s_nop 0
	v_pk_mul_f32 v[158:159], v[212:213], v[158:159]
	s_nop 0
	v_pk_mul_f32 v[212:213], v[210:211], v[158:159]
	v_pk_fma_f32 v[158:159], v[210:211], v[158:159], v[210:211] neg_lo:[1,0,0] neg_hi:[1,0,0]
	s_nop 0
	v_cndmask_b32_e32 v165, v158, v212, vcc
	v_cmp_gt_f32_e32 vcc, 0, v211
	v_mul_f32_e32 v158, v152, v161
	v_mul_f32_e32 v161, v153, v163
	v_cndmask_b32_e32 v159, v159, v213, vcc
	v_mul_f32_e32 v159, v155, v159
	v_cvt_pk_bf16_f32 v158, v158, v161
	v_mul_f32_e32 v161, v154, v165
	v_cvt_pk_bf16_f32 v159, v161, v159
	s_and_saveexec_b64 s[36:37], s[44:45]
	s_mov_b32 s96, s10
	s_movk_i32 s71, 0x4000
	s_movk_i32 s79, 0x2000
	s_cbranch_execz .LBB0_1551
	v_mov_b64_e32 v[210:211], s[56:57]
	s_movk_i32 s10, 0x2c00
	v_mad_i64_i32 v[210:211], s[50:51], v190, s10, v[210:211]
	v_lshl_add_u64 v[210:211], v[188:189], 1, v[210:211]
	global_store_dwordx4 v[210:211], v[156:159], off

.LBB0_1553:
	s_or_b64 exec, exec, s[36:37]
	s_nop 1
	v_pk_fma_f32 v[152:153], v[148:149], v[166:167], v[88:89] op_sel_hi:[1,0,1]
	v_pk_fma_f32 v[148:149], v[144:145], v[166:167], v[84:85] op_sel_hi:[1,0,1]
	v_mov_b32_dpp v144, v204 row_ror:1 row_mask:0xf bank_mask:0xf bound_ctrl:1
	v_mov_b32_dpp v145, v205 row_ror:1 row_mask:0xf bank_mask:0xf bound_ctrl:1
	v_mov_b32_dpp v154, v152 row_ror:15 row_mask:0xf bank_mask:0xf bound_ctrl:1
	v_mov_b32_dpp v144, v174 row_shr:1 row_mask:0xf bank_mask:0xf
	v_mov_b32_dpp v155, v153 row_ror:15 row_mask:0xf bank_mask:0xf bound_ctrl:1
	v_mov_b32_dpp v145, v175 row_shr:1 row_mask:0xf bank_mask:0xf
	v_pk_mul_f32 v[158:159], v[80:81], v[174:175]
	v_mov_b32_dpp v154, v174 row_shl:1 row_mask:0xf bank_mask:0xf
	v_mov_b32_dpp v155, v175 row_shl:1 row_mask:0xf bank_mask:0xf
	v_pk_fma_f32 v[144:145], v[68:69], v[144:145], v[158:159]
	v_pk_fma_f32 v[150:151], v[150:151], v[166:167], v[90:91] op_sel_hi:[1,0,1]
	v_pk_fma_f32 v[144:145], v[72:73], v[154:155], v[144:145]
	v_pk_mul_f32 v[156:157], v[82:83], v[172:173]
	v_pk_add_f32 v[154:155], v[76:77], v[144:145]
	v_mov_b32_dpp v144, v202 row_ror:1 row_mask:0xf bank_mask:0xf bound_ctrl:1
	v_mov_b32_dpp v145, v203 row_ror:1 row_mask:0xf bank_mask:0xf bound_ctrl:1
	v_mov_b32_dpp v158, v150 row_ror:15 row_mask:0xf bank_mask:0xf bound_ctrl:1
	v_mov_b32_dpp v144, v172 row_shr:1 row_mask:0xf bank_mask:0xf
	v_mov_b32_dpp v159, v151 row_ror:15 row_mask:0xf bank_mask:0xf bound_ctrl:1
	v_mov_b32_dpp v145, v173 row_shr:1 row_mask:0xf bank_mask:0xf
	v_mov_b32_dpp v158, v172 row_shl:1 row_mask:0xf bank_mask:0xf
	v_mov_b32_dpp v159, v173 row_shl:1 row_mask:0xf bank_mask:0xf
	v_pk_fma_f32 v[144:145], v[70:71], v[144:145], v[156:157]
	s_mov_b32 s10, 0xbf3a00e3
	v_pk_fma_f32 v[144:145], v[74:75], v[158:159], v[144:145]
	v_cmp_gt_f32_e32 vcc, 0, v154
	v_pk_add_f32 v[156:157], v[78:79], v[144:145]
	v_and_b32_e32 v145, 0x7fffffff, v155
	v_and_b32_e32 v144, 0x7fffffff, v154
	v_pk_fma_f32 v[144:145], v[144:145], s[26:27], 1.0 op_sel_hi:[1,0,0]
	s_nop 1
	v_pk_fma_f32 v[142:143], v[142:143], v[162:163], v[90:91] op_sel_hi:[1,0,1]
	v_rcp_f32_e32 v158, v144
	v_rcp_f32_e32 v159, v145
	v_mov_b64_e32 v[144:145], s[10:11]
	v_pk_fma_f32 v[140:141], v[140:141], v[162:163], v[88:89] op_sel_hi:[1,0,1]
	v_pk_fma_f32 v[138:139], v[138:139], v[162:163], v[86:87] op_sel_hi:[1,0,1]
	v_pk_fma_f32 v[202:203], v[158:159], s[72:73], v[144:145] op_sel_hi:[1,0,0]
	v_pk_fma_f32 v[136:137], v[136:137], v[162:163], v[84:85] op_sel_hi:[1,0,1]
	v_pk_fma_f32 v[202:203], v[158:159], v[202:203], s[16:17] op_sel_hi:[1,1,0]
	v_mov_b32_e32 v197, v196
	v_pk_fma_f32 v[202:203], v[158:159], v[202:203], s[78:79] op_sel_hi:[1,1,0]
	v_pk_fma_f32 v[132:133], v[132:133], v[196:197], v[64:65]
	v_pk_fma_f32 v[202:203], v[158:159], v[202:203], s[0:1] op_sel_hi:[1,1,0]
	v_pk_fma_f32 v[146:147], v[146:147], v[166:167], v[86:87] op_sel_hi:[1,0,1]
	v_pk_mul_f32 v[158:159], v[158:159], v[202:203]
	v_pk_mul_f32 v[202:203], v[154:155], v[154:155]
	v_pk_fma_f32 v[128:129], v[128:129], v[196:197], v[44:45]
	v_pk_mul_f32 v[202:203], v[202:203], s[28:29] op_sel_hi:[1,0]
	s_movk_i32 s10, 0x2c00
	v_exp_f32_e32 v202, v202
	v_exp_f32_e32 v203, v203
	v_pk_fma_f32 v[124:125], v[124:125], v[166:167], v[64:65] op_sel_hi:[1,0,1]
	v_pk_fma_f32 v[126:127], v[126:127], v[166:167], v[66:67] op_sel_hi:[1,0,1]
	v_pk_fma_f32 v[120:121], v[120:121], v[166:167], v[44:45] op_sel_hi:[1,0,1]
	v_pk_mul_f32 v[158:159], v[202:203], v[158:159]
	v_pk_fma_f32 v[122:123], v[122:123], v[166:167], v[46:47] op_sel_hi:[1,0,1]
	v_pk_mul_f32 v[202:203], v[154:155], v[158:159]
	v_pk_fma_f32 v[158:159], v[154:155], v[158:159], v[154:155] neg_lo:[1,0,0] neg_hi:[1,0,0]
	v_and_b32_e32 v154, 0x7fffffff, v156
	v_cndmask_b32_e32 v161, v158, v202, vcc
	v_cmp_gt_f32_e32 vcc, 0, v155
	v_and_b32_e32 v155, 0x7fffffff, v157
	v_pk_fma_f32 v[154:155], v[154:155], s[26:27], 1.0 op_sel_hi:[1,0,0]
	v_cndmask_b32_e32 v163, v159, v203, vcc
	v_rcp_f32_e32 v154, v154
	v_rcp_f32_e32 v155, v155
	v_cmp_gt_f32_e32 vcc, 0, v156
	v_mul_f32_e32 v132, v132, v161
	v_mul_f32_e32 v133, v133, v163
	v_pk_fma_f32 v[158:159], v[154:155], s[72:73], v[144:145] op_sel_hi:[1,0,0]
	v_cvt_pk_bf16_f32 v132, v132, v133
	s_nop 0
	v_pk_fma_f32 v[158:159], v[154:155], v[158:159], s[16:17] op_sel_hi:[1,1,0]
	s_nop 0
	v_pk_fma_f32 v[158:159], v[154:155], v[158:159], s[78:79] op_sel_hi:[1,1,0]
	s_nop 0
	v_pk_fma_f32 v[158:159], v[154:155], v[158:159], s[0:1] op_sel_hi:[1,1,0]
	s_nop 0
	v_pk_mul_f32 v[154:155], v[154:155], v[158:159]
	v_pk_mul_f32 v[158:159], v[156:157], v[156:157]
	s_nop 0
	v_pk_mul_f32 v[158:159], v[158:159], s[28:29] op_sel_hi:[1,0]
	s_nop 0
	v_exp_f32_e32 v158, v158
	v_exp_f32_e32 v159, v159
	s_nop 0
	v_pk_mul_f32 v[154:155], v[158:159], v[154:155]
	s_nop 0
	v_pk_mul_f32 v[158:159], v[156:157], v[154:155]
	v_pk_fma_f32 v[154:155], v[156:157], v[154:155], v[156:157] neg_lo:[1,0,0] neg_hi:[1,0,0]
	s_nop 0
	v_cndmask_b32_e32 v156, v154, v158, vcc
	v_cmp_gt_f32_e32 vcc, 0, v157
	v_mov_b32_e32 v154, v196
	s_nop 0
	v_cndmask_b32_e32 v157, v155, v159, vcc
	v_mov_b32_e32 v155, v196
	v_pk_fma_f32 v[134:135], v[134:135], v[154:155], v[66:67]
	v_pk_mul_f32 v[158:159], v[62:63], v[168:169]
	v_mul_f32_e32 v133, v134, v156
	v_mul_f32_e32 v134, v135, v157
	v_cvt_pk_bf16_f32 v133, v133, v134
	v_mov_b32_dpp v135, v201 row_ror:1 row_mask:0xf bank_mask:0xf bound_ctrl:1
	v_mov_b32_dpp v156, v148 row_ror:15 row_mask:0xf bank_mask:0xf bound_ctrl:1
	v_mov_b32_dpp v134, v200 row_ror:1 row_mask:0xf bank_mask:0xf bound_ctrl:1
	v_mov_b32_dpp v157, v149 row_ror:15 row_mask:0xf bank_mask:0xf bound_ctrl:1
	v_mov_b32_dpp v135, v171 row_shr:1 row_mask:0xf bank_mask:0xf
	v_mov_b32_dpp v134, v170 row_shr:1 row_mask:0xf bank_mask:0xf
	v_pk_mul_f32 v[200:201], v[60:61], v[170:171]
	v_mov_b32_dpp v156, v170 row_shl:1 row_mask:0xf bank_mask:0xf
	v_mov_b32_dpp v157, v171 row_shl:1 row_mask:0xf bank_mask:0xf
	v_pk_fma_f32 v[134:135], v[48:49], v[134:135], v[200:201]
	v_pk_fma_f32 v[130:131], v[130:131], v[154:155], v[46:47]
	v_pk_fma_f32 v[134:135], v[52:53], v[156:157], v[134:135]
	v_mov_b32_dpp v156, v198 row_ror:1 row_mask:0xf bank_mask:0xf bound_ctrl:1
	v_mov_b32_dpp v157, v199 row_ror:1 row_mask:0xf bank_mask:0xf bound_ctrl:1
	v_pk_add_f32 v[134:135], v[56:57], v[134:135]
	v_mov_b32_dpp v156, v168 row_shr:1 row_mask:0xf bank_mask:0xf
	v_mov_b32_dpp v157, v169 row_shr:1 row_mask:0xf bank_mask:0xf
	v_pk_fma_f32 v[156:157], v[50:51], v[156:157], v[158:159]
	v_and_b32_e32 v159, 0x7fffffff, v135
	v_and_b32_e32 v158, 0x7fffffff, v134
	v_pk_fma_f32 v[158:159], v[158:159], s[26:27], 1.0 op_sel_hi:[1,0,0]
	v_mov_b32_dpp v198, v146 row_ror:15 row_mask:0xf bank_mask:0xf bound_ctrl:1
	v_rcp_f32_e32 v158, v158
	v_rcp_f32_e32 v159, v159
	v_mov_b32_dpp v199, v147 row_ror:15 row_mask:0xf bank_mask:0xf bound_ctrl:1
	v_mov_b32_dpp v198, v168 row_shl:1 row_mask:0xf bank_mask:0xf
	v_cmp_gt_f32_e32 vcc, 0, v134
	v_mov_b32_dpp v199, v169 row_shl:1 row_mask:0xf bank_mask:0xf
	v_pk_fma_f32 v[156:157], v[54:55], v[198:199], v[156:157]
	v_pk_fma_f32 v[198:199], v[158:159], s[72:73], v[144:145] op_sel_hi:[1,0,0]
	v_pk_add_f32 v[156:157], v[58:59], v[156:157]
	v_pk_fma_f32 v[198:199], v[158:159], v[198:199], s[16:17] op_sel_hi:[1,1,0]
	s_nop 0
	v_pk_fma_f32 v[198:199], v[158:159], v[198:199], s[78:79] op_sel_hi:[1,1,0]
	s_nop 0
	v_pk_fma_f32 v[198:199], v[158:159], v[198:199], s[0:1] op_sel_hi:[1,1,0]
	s_nop 0
	v_pk_mul_f32 v[158:159], v[158:159], v[198:199]
	v_pk_mul_f32 v[198:199], v[134:135], v[134:135]
	s_nop 0
	v_pk_mul_f32 v[198:199], v[198:199], s[28:29] op_sel_hi:[1,0]
	s_nop 0
	v_exp_f32_e32 v198, v198
	v_exp_f32_e32 v199, v199
	s_nop 0
	v_pk_mul_f32 v[158:159], v[198:199], v[158:159]
	s_nop 0
	v_pk_mul_f32 v[198:199], v[134:135], v[158:159]
	v_pk_fma_f32 v[158:159], v[134:135], v[158:159], v[134:135] neg_lo:[1,0,0] neg_hi:[1,0,0]
	v_and_b32_e32 v134, 0x7fffffff, v156
	v_cndmask_b32_e32 v161, v158, v198, vcc
	v_cmp_gt_f32_e32 vcc, 0, v135
	v_and_b32_e32 v135, 0x7fffffff, v157
	v_pk_fma_f32 v[134:135], v[134:135], s[26:27], 1.0 op_sel_hi:[1,0,0]
	v_cndmask_b32_e32 v163, v159, v199, vcc
	v_rcp_f32_e32 v134, v134
	v_rcp_f32_e32 v135, v135
	v_cmp_gt_f32_e32 vcc, 0, v156
	v_mul_f32_e32 v128, v128, v161
	v_mul_f32_e32 v129, v129, v163
	v_pk_fma_f32 v[158:159], v[134:135], s[72:73], v[144:145] op_sel_hi:[1,0,0]
	v_pk_fma_f32 v[114:115], v[114:115], v[162:163], v[46:47] op_sel_hi:[1,0,1]
	v_pk_fma_f32 v[158:159], v[134:135], v[158:159], s[16:17] op_sel_hi:[1,1,0]
	v_pk_fma_f32 v[112:113], v[112:113], v[162:163], v[44:45] op_sel_hi:[1,0,1]
	v_pk_fma_f32 v[158:159], v[134:135], v[158:159], s[78:79] op_sel_hi:[1,1,0]
	s_nop 0
	v_pk_fma_f32 v[158:159], v[134:135], v[158:159], s[0:1] op_sel_hi:[1,1,0]
	s_nop 0
	v_pk_mul_f32 v[134:135], v[134:135], v[158:159]
	v_pk_mul_f32 v[158:159], v[156:157], v[156:157]
	s_nop 0
	v_pk_mul_f32 v[158:159], v[158:159], s[28:29] op_sel_hi:[1,0]
	s_nop 0
	v_exp_f32_e32 v158, v158
	v_exp_f32_e32 v159, v159
	s_nop 0
	v_pk_mul_f32 v[134:135], v[158:159], v[134:135]
	s_nop 0
	v_pk_mul_f32 v[158:159], v[156:157], v[134:135]
	v_pk_fma_f32 v[134:135], v[156:157], v[134:135], v[156:157] neg_lo:[1,0,0] neg_hi:[1,0,0]
	s_nop 0
	v_cndmask_b32_e32 v156, v134, v158, vcc
	v_cmp_gt_f32_e32 vcc, 0, v157
	v_cvt_pk_bf16_f32 v134, v128, v129
	v_mul_f32_e32 v128, v130, v156
	v_pk_mul_f32 v[156:157], v[80:81], v[152:153]
	v_cndmask_b32_e32 v135, v135, v159, vcc
	v_mul_f32_e32 v129, v131, v135
	v_mov_b64_e32 v[130:131], s[56:57]
	v_cvt_pk_bf16_f32 v135, v128, v129
	v_mad_i64_i32 v[154:155], s[36:37], v194, s10, v[130:131]
	v_lshlrev_b64 v[128:129], 1, v[188:189]
	v_lshl_add_u64 v[154:155], v[154:155], 0, v[128:129]
	global_store_dwordx4 v[154:155], v[132:135], off
	v_pk_mul_f32 v[154:155], v[82:83], v[150:151]
	s_nop 0
	v_mov_b32_dpp v132, v174 row_ror:1 row_mask:0xf bank_mask:0xf bound_ctrl:1
	v_mov_b32_dpp v133, v175 row_ror:1 row_mask:0xf bank_mask:0xf bound_ctrl:1
	v_mov_b32_dpp v134, v140 row_ror:15 row_mask:0xf bank_mask:0xf bound_ctrl:1
	v_mov_b32_dpp v132, v152 row_shr:1 row_mask:0xf bank_mask:0xf
	v_mov_b32_dpp v135, v141 row_ror:15 row_mask:0xf bank_mask:0xf bound_ctrl:1
	v_mov_b32_dpp v133, v153 row_shr:1 row_mask:0xf bank_mask:0xf
	v_mov_b32_dpp v134, v152 row_shl:1 row_mask:0xf bank_mask:0xf
	v_mov_b32_dpp v135, v153 row_shl:1 row_mask:0xf bank_mask:0xf
	v_pk_fma_f32 v[132:133], v[68:69], v[132:133], v[156:157]
	v_mov_b32_dpp v156, v142 row_ror:15 row_mask:0xf bank_mask:0xf bound_ctrl:1
	v_pk_fma_f32 v[132:133], v[72:73], v[134:135], v[132:133]
	v_mov_b32_dpp v134, v172 row_ror:1 row_mask:0xf bank_mask:0xf bound_ctrl:1
	v_mov_b32_dpp v135, v173 row_ror:1 row_mask:0xf bank_mask:0xf bound_ctrl:1
	v_pk_add_f32 v[132:133], v[76:77], v[132:133]
	v_mov_b32_dpp v134, v150 row_shr:1 row_mask:0xf bank_mask:0xf
	v_mov_b32_dpp v135, v151 row_shr:1 row_mask:0xf bank_mask:0xf
	v_pk_fma_f32 v[134:135], v[70:71], v[134:135], v[154:155]
	v_and_b32_e32 v155, 0x7fffffff, v133
	v_and_b32_e32 v154, 0x7fffffff, v132
	v_pk_fma_f32 v[154:155], v[154:155], s[26:27], 1.0 op_sel_hi:[1,0,0]
	v_mov_b32_dpp v157, v143 row_ror:15 row_mask:0xf bank_mask:0xf bound_ctrl:1
	v_rcp_f32_e32 v154, v154
	v_rcp_f32_e32 v155, v155
	v_mov_b32_dpp v156, v150 row_shl:1 row_mask:0xf bank_mask:0xf
	v_mov_b32_dpp v157, v151 row_shl:1 row_mask:0xf bank_mask:0xf
	v_pk_fma_f32 v[134:135], v[74:75], v[156:157], v[134:135]
	v_pk_fma_f32 v[156:157], v[154:155], s[72:73], v[144:145] op_sel_hi:[1,0,0]
	v_pk_add_f32 v[134:135], v[78:79], v[134:135]
	v_pk_fma_f32 v[156:157], v[154:155], v[156:157], s[16:17] op_sel_hi:[1,1,0]
	v_cmp_gt_f32_e32 vcc, 0, v132
	v_pk_fma_f32 v[156:157], v[154:155], v[156:157], s[78:79] op_sel_hi:[1,1,0]
	s_nop 0
	v_pk_fma_f32 v[156:157], v[154:155], v[156:157], s[0:1] op_sel_hi:[1,1,0]
	s_nop 0
	v_pk_mul_f32 v[154:155], v[154:155], v[156:157]
	v_pk_mul_f32 v[156:157], v[132:133], v[132:133]
	s_nop 0
	v_pk_mul_f32 v[156:157], v[156:157], s[28:29] op_sel_hi:[1,0]
	s_nop 0
	v_exp_f32_e32 v156, v156
	v_exp_f32_e32 v157, v157
	s_nop 0
	v_pk_mul_f32 v[154:155], v[156:157], v[154:155]
	s_nop 0
	v_pk_mul_f32 v[156:157], v[132:133], v[154:155]
	v_pk_fma_f32 v[154:155], v[132:133], v[154:155], v[132:133] neg_lo:[1,0,0] neg_hi:[1,0,0]
	v_and_b32_e32 v132, 0x7fffffff, v134
	v_cndmask_b32_e32 v156, v154, v156, vcc
	v_cmp_gt_f32_e32 vcc, 0, v133
	v_and_b32_e32 v133, 0x7fffffff, v135
	v_pk_fma_f32 v[132:133], v[132:133], s[26:27], 1.0 op_sel_hi:[1,0,0]
	v_cndmask_b32_e32 v157, v155, v157, vcc
	v_rcp_f32_e32 v132, v132
	v_rcp_f32_e32 v133, v133
	v_cmp_gt_f32_e32 vcc, 0, v134
	v_mul_f32_e32 v124, v124, v156
	v_mul_f32_e32 v125, v125, v157
	v_pk_fma_f32 v[154:155], v[132:133], s[72:73], v[144:145] op_sel_hi:[1,0,0]
	v_cvt_pk_bf16_f32 v124, v124, v125
	s_nop 0
	v_pk_fma_f32 v[154:155], v[132:133], v[154:155], s[16:17] op_sel_hi:[1,1,0]
	s_nop 0
	v_pk_fma_f32 v[154:155], v[132:133], v[154:155], s[78:79] op_sel_hi:[1,1,0]
	s_nop 0
	v_pk_fma_f32 v[154:155], v[132:133], v[154:155], s[0:1] op_sel_hi:[1,1,0]
	s_nop 0
	v_pk_mul_f32 v[132:133], v[132:133], v[154:155]
	v_pk_mul_f32 v[154:155], v[134:135], v[134:135]
	s_nop 0
	v_pk_mul_f32 v[154:155], v[154:155], s[28:29] op_sel_hi:[1,0]
	s_nop 0
	v_exp_f32_e32 v154, v154
	v_exp_f32_e32 v155, v155
	s_nop 0
	v_pk_mul_f32 v[132:133], v[154:155], v[132:133]
	s_nop 0
	v_pk_mul_f32 v[154:155], v[134:135], v[132:133]
	v_pk_fma_f32 v[132:133], v[134:135], v[132:133], v[134:135] neg_lo:[1,0,0] neg_hi:[1,0,0]
	s_nop 0
	v_cndmask_b32_e32 v132, v132, v154, vcc
	v_cmp_gt_f32_e32 vcc, 0, v135
	v_mul_f32_e32 v125, v126, v132
	v_mov_b32_dpp v132, v136 row_ror:15 row_mask:0xf bank_mask:0xf bound_ctrl:1
	v_cndmask_b32_e32 v133, v133, v155, vcc
	v_mul_f32_e32 v126, v127, v133
	v_cvt_pk_bf16_f32 v125, v125, v126
	v_mov_b32_dpp v127, v171 row_ror:1 row_mask:0xf bank_mask:0xf bound_ctrl:1
	v_mov_b32_dpp v133, v137 row_ror:15 row_mask:0xf bank_mask:0xf bound_ctrl:1
	v_mov_b32_dpp v126, v170 row_ror:1 row_mask:0xf bank_mask:0xf bound_ctrl:1
	v_mov_b32_dpp v127, v149 row_shr:1 row_mask:0xf bank_mask:0xf
	v_pk_mul_f32 v[154:155], v[60:61], v[148:149]
	v_mov_b32_dpp v126, v148 row_shr:1 row_mask:0xf bank_mask:0xf
	v_mov_b32_dpp v132, v148 row_shl:1 row_mask:0xf bank_mask:0xf
	v_mov_b32_dpp v133, v149 row_shl:1 row_mask:0xf bank_mask:0xf
	v_pk_fma_f32 v[126:127], v[48:49], v[126:127], v[154:155]
	v_pk_mul_f32 v[134:135], v[62:63], v[146:147]
	v_pk_fma_f32 v[126:127], v[52:53], v[132:133], v[126:127]
	v_mov_b32_dpp v132, v168 row_ror:1 row_mask:0xf bank_mask:0xf bound_ctrl:1
	v_mov_b32_dpp v133, v169 row_ror:1 row_mask:0xf bank_mask:0xf bound_ctrl:1
	v_pk_add_f32 v[126:127], v[56:57], v[126:127]
	v_mov_b32_dpp v132, v146 row_shr:1 row_mask:0xf bank_mask:0xf
	v_mov_b32_dpp v133, v147 row_shr:1 row_mask:0xf bank_mask:0xf
	v_pk_fma_f32 v[132:133], v[50:51], v[132:133], v[134:135]
	v_and_b32_e32 v135, 0x7fffffff, v127
	v_and_b32_e32 v134, 0x7fffffff, v126
	v_pk_fma_f32 v[134:135], v[134:135], s[26:27], 1.0 op_sel_hi:[1,0,0]
	v_mov_b32_dpp v154, v138 row_ror:15 row_mask:0xf bank_mask:0xf bound_ctrl:1
	v_rcp_f32_e32 v134, v134
	v_rcp_f32_e32 v135, v135
	v_mov_b32_dpp v155, v139 row_ror:15 row_mask:0xf bank_mask:0xf bound_ctrl:1
	v_mov_b32_dpp v154, v146 row_shl:1 row_mask:0xf bank_mask:0xf
	v_cmp_gt_f32_e32 vcc, 0, v126
	v_mov_b32_dpp v155, v147 row_shl:1 row_mask:0xf bank_mask:0xf
	v_pk_fma_f32 v[132:133], v[54:55], v[154:155], v[132:133]
	v_pk_fma_f32 v[154:155], v[134:135], s[72:73], v[144:145] op_sel_hi:[1,0,0]
	v_pk_add_f32 v[132:133], v[58:59], v[132:133]
	v_pk_fma_f32 v[154:155], v[134:135], v[154:155], s[16:17] op_sel_hi:[1,1,0]
	s_nop 0
	v_pk_fma_f32 v[154:155], v[134:135], v[154:155], s[78:79] op_sel_hi:[1,1,0]
	s_nop 0
	v_pk_fma_f32 v[154:155], v[134:135], v[154:155], s[0:1] op_sel_hi:[1,1,0]
	s_nop 0
	v_pk_mul_f32 v[134:135], v[134:135], v[154:155]
	v_pk_mul_f32 v[154:155], v[126:127], v[126:127]
	s_nop 0
	v_pk_mul_f32 v[154:155], v[154:155], s[28:29] op_sel_hi:[1,0]
	s_nop 0
	v_exp_f32_e32 v154, v154
	v_exp_f32_e32 v155, v155
	s_nop 0
	v_pk_mul_f32 v[134:135], v[154:155], v[134:135]
	s_nop 0
	v_pk_mul_f32 v[154:155], v[126:127], v[134:135]
	v_pk_fma_f32 v[134:135], v[126:127], v[134:135], v[126:127] neg_lo:[1,0,0] neg_hi:[1,0,0]
	v_and_b32_e32 v126, 0x7fffffff, v132
	v_cndmask_b32_e32 v154, v134, v154, vcc
	v_cmp_gt_f32_e32 vcc, 0, v127
	v_and_b32_e32 v127, 0x7fffffff, v133
	v_pk_fma_f32 v[126:127], v[126:127], s[26:27], 1.0 op_sel_hi:[1,0,0]
	v_cndmask_b32_e32 v155, v135, v155, vcc
	v_rcp_f32_e32 v126, v126
	v_rcp_f32_e32 v127, v127
	v_cmp_gt_f32_e32 vcc, 0, v132
	v_mul_f32_e32 v120, v120, v154
	v_mul_f32_e32 v121, v121, v155
	v_pk_fma_f32 v[134:135], v[126:127], s[72:73], v[144:145] op_sel_hi:[1,0,0]
	s_movk_i32 s27, 0x2c00
	v_pk_fma_f32 v[134:135], v[126:127], v[134:135], s[16:17] op_sel_hi:[1,1,0]
	s_nop 0
	v_pk_fma_f32 v[134:135], v[126:127], v[134:135], s[78:79] op_sel_hi:[1,1,0]
	s_nop 0
	v_pk_fma_f32 v[134:135], v[126:127], v[134:135], s[0:1] op_sel_hi:[1,1,0]
	s_nop 0
	v_pk_mul_f32 v[126:127], v[126:127], v[134:135]
	v_pk_mul_f32 v[134:135], v[132:133], v[132:133]
	s_nop 0
	v_pk_mul_f32 v[134:135], v[134:135], s[28:29] op_sel_hi:[1,0]
	s_nop 0
	v_exp_f32_e32 v134, v134
	v_exp_f32_e32 v135, v135
	s_nop 0
	v_pk_mul_f32 v[126:127], v[134:135], v[126:127]
	s_nop 0
	v_pk_mul_f32 v[134:135], v[132:133], v[126:127]
	v_pk_fma_f32 v[126:127], v[132:133], v[126:127], v[132:133] neg_lo:[1,0,0] neg_hi:[1,0,0]
	s_nop 0
	v_cndmask_b32_e32 v132, v126, v134, vcc
	v_cmp_gt_f32_e32 vcc, 0, v133
	v_cvt_pk_bf16_f32 v126, v120, v121
	v_mul_f32_e32 v120, v122, v132
	v_mov_b32_e32 v122, v209
	v_cndmask_b32_e32 v127, v127, v135, vcc
	v_mul_f32_e32 v121, v123, v127
	v_cvt_pk_bf16_f32 v127, v120, v121
	v_mad_i64_i32 v[120:121], s[36:37], v164, s10, v[130:131]
	v_lshl_add_u64 v[120:121], v[120:121], 0, v[128:129]
	global_store_dwordx4 v[120:121], v[124:127], off
	v_mov_b32_e32 v123, v209
	v_mov_b32_dpp v120, v152 row_ror:1 row_mask:0xf bank_mask:0xf bound_ctrl:1
	v_mov_b32_dpp v121, v153 row_ror:1 row_mask:0xf bank_mask:0xf bound_ctrl:1
	v_pk_mul_f32 v[126:127], v[80:81], v[140:141]
	v_mov_b32_dpp v120, v140 row_shr:1 row_mask:0xf bank_mask:0xf
	v_mov_b32_dpp v121, v141 row_shr:1 row_mask:0xf bank_mask:0xf
	v_mov_b32_dpp v122, v140 row_shl:1 row_mask:0xf bank_mask:0xf
	v_mov_b32_dpp v123, v141 row_shl:1 row_mask:0xf bank_mask:0xf
	v_pk_fma_f32 v[120:121], v[68:69], v[120:121], v[126:127]
	v_pk_mul_f32 v[124:125], v[82:83], v[142:143]
	v_pk_fma_f32 v[120:121], v[72:73], v[122:123], v[120:121]
	v_mov_b32_dpp v122, v150 row_ror:1 row_mask:0xf bank_mask:0xf bound_ctrl:1
	v_mov_b32_dpp v123, v151 row_ror:1 row_mask:0xf bank_mask:0xf bound_ctrl:1
	v_pk_add_f32 v[120:121], v[76:77], v[120:121]
	v_mov_b32_dpp v122, v142 row_shr:1 row_mask:0xf bank_mask:0xf
	v_mov_b32_dpp v123, v143 row_shr:1 row_mask:0xf bank_mask:0xf
	v_pk_fma_f32 v[122:123], v[70:71], v[122:123], v[124:125]
	v_and_b32_e32 v125, 0x7fffffff, v121
	v_and_b32_e32 v124, 0x7fffffff, v120
	v_pk_fma_f32 v[124:125], v[124:125], s[26:27], 1.0 op_sel_hi:[1,0,0]
	v_mov_b32_e32 v126, v209
	v_rcp_f32_e32 v124, v124
	v_rcp_f32_e32 v125, v125
	v_mov_b32_e32 v127, v209
	v_mov_b32_dpp v126, v142 row_shl:1 row_mask:0xf bank_mask:0xf
	v_cmp_gt_f32_e32 vcc, 0, v120
	v_mov_b32_dpp v127, v143 row_shl:1 row_mask:0xf bank_mask:0xf
	v_pk_fma_f32 v[122:123], v[74:75], v[126:127], v[122:123]
	v_pk_fma_f32 v[126:127], v[124:125], s[72:73], v[144:145] op_sel_hi:[1,0,0]
	v_pk_add_f32 v[122:123], v[78:79], v[122:123]
	v_pk_fma_f32 v[126:127], v[124:125], v[126:127], s[16:17] op_sel_hi:[1,1,0]
	v_pk_mul_f32 v[130:131], v[60:61], v[136:137]
	v_pk_fma_f32 v[126:127], v[124:125], v[126:127], s[78:79] op_sel_hi:[1,1,0]
	s_nop 0
	v_pk_fma_f32 v[126:127], v[124:125], v[126:127], s[0:1] op_sel_hi:[1,1,0]
	s_nop 0
	v_pk_mul_f32 v[124:125], v[124:125], v[126:127]
	v_pk_mul_f32 v[126:127], v[120:121], v[120:121]
	s_nop 0
	v_pk_mul_f32 v[126:127], v[126:127], s[28:29] op_sel_hi:[1,0]
	s_nop 0
	v_exp_f32_e32 v126, v126
	v_exp_f32_e32 v127, v127
	s_nop 0
	v_pk_mul_f32 v[124:125], v[126:127], v[124:125]
	s_nop 0
	v_pk_mul_f32 v[126:127], v[120:121], v[124:125]
	v_pk_fma_f32 v[124:125], v[120:121], v[124:125], v[120:121] neg_lo:[1,0,0] neg_hi:[1,0,0]
	v_and_b32_e32 v120, 0x7fffffff, v122
	v_cndmask_b32_e32 v126, v124, v126, vcc
	v_cmp_gt_f32_e32 vcc, 0, v121
	v_and_b32_e32 v121, 0x7fffffff, v123
	v_pk_fma_f32 v[120:121], v[120:121], s[26:27], 1.0 op_sel_hi:[1,0,0]
	v_cndmask_b32_e32 v127, v125, v127, vcc
	v_rcp_f32_e32 v120, v120
	v_rcp_f32_e32 v121, v121
	v_cmp_gt_f32_e32 vcc, 0, v122
	v_pk_fma_f32 v[124:125], v[120:121], s[72:73], v[144:145] op_sel_hi:[1,0,0]
	s_nop 0
	v_pk_fma_f32 v[124:125], v[120:121], v[124:125], s[16:17] op_sel_hi:[1,1,0]
	s_nop 0
	v_pk_fma_f32 v[124:125], v[120:121], v[124:125], s[78:79] op_sel_hi:[1,1,0]
	s_nop 0
	v_pk_fma_f32 v[124:125], v[120:121], v[124:125], s[0:1] op_sel_hi:[1,1,0]
	s_nop 0
	v_pk_mul_f32 v[120:121], v[120:121], v[124:125]
	v_pk_mul_f32 v[124:125], v[122:123], v[122:123]
	s_nop 0
	v_pk_mul_f32 v[124:125], v[124:125], s[28:29] op_sel_hi:[1,0]
	s_nop 0
	v_exp_f32_e32 v124, v124
	v_exp_f32_e32 v125, v125
	s_nop 0
	v_pk_mul_f32 v[120:121], v[124:125], v[120:121]
	s_nop 0
	v_pk_mul_f32 v[124:125], v[122:123], v[120:121]
	v_pk_fma_f32 v[120:121], v[122:123], v[120:121], v[122:123] neg_lo:[1,0,0] neg_hi:[1,0,0]
	s_nop 0
	v_cndmask_b32_e32 v124, v120, v124, vcc
	v_cmp_gt_f32_e32 vcc, 0, v123
	v_pk_fma_f32 v[122:123], v[116:117], v[162:163], v[64:65] op_sel_hi:[1,0,1]
	s_nop 0
	v_cndmask_b32_e32 v125, v121, v125, vcc
	v_pk_fma_f32 v[120:121], v[118:119], v[162:163], v[66:67] op_sel_hi:[1,0,1]
	v_mul_f32_e32 v116, v122, v126
	v_mul_f32_e32 v117, v123, v127
	v_cvt_pk_bf16_f32 v116, v116, v117
	v_mul_f32_e32 v117, v120, v124
	v_mul_f32_e32 v118, v121, v125
	v_cvt_pk_bf16_f32 v117, v117, v118
	v_mov_b32_dpp v119, v149 row_ror:1 row_mask:0xf bank_mask:0xf bound_ctrl:1
	v_mov_b32_e32 v124, v209
	v_mov_b32_dpp v118, v148 row_ror:1 row_mask:0xf bank_mask:0xf bound_ctrl:1
	v_mov_b32_dpp v119, v137 row_shr:1 row_mask:0xf bank_mask:0xf
	v_mov_b32_e32 v125, v209
	v_mov_b32_dpp v118, v136 row_shr:1 row_mask:0xf bank_mask:0xf
	v_mov_b32_dpp v124, v136 row_shl:1 row_mask:0xf bank_mask:0xf
	v_mov_b32_dpp v125, v137 row_shl:1 row_mask:0xf bank_mask:0xf
	v_pk_fma_f32 v[118:119], v[48:49], v[118:119], v[130:131]
	v_pk_mul_f32 v[126:127], v[62:63], v[138:139]
	v_pk_fma_f32 v[118:119], v[52:53], v[124:125], v[118:119]
	v_mov_b32_dpp v124, v146 row_ror:1 row_mask:0xf bank_mask:0xf bound_ctrl:1
	v_mov_b32_dpp v125, v147 row_ror:1 row_mask:0xf bank_mask:0xf bound_ctrl:1
	v_pk_add_f32 v[118:119], v[56:57], v[118:119]
	v_mov_b32_dpp v124, v138 row_shr:1 row_mask:0xf bank_mask:0xf
	v_mov_b32_dpp v125, v139 row_shr:1 row_mask:0xf bank_mask:0xf
	v_pk_fma_f32 v[124:125], v[50:51], v[124:125], v[126:127]
	v_and_b32_e32 v127, 0x7fffffff, v119
	v_and_b32_e32 v126, 0x7fffffff, v118
	v_pk_fma_f32 v[126:127], v[126:127], s[26:27], 1.0 op_sel_hi:[1,0,0]
	v_mov_b32_e32 v130, v209
	v_rcp_f32_e32 v126, v126
	v_rcp_f32_e32 v127, v127
	v_mov_b32_e32 v131, v209
	v_mov_b32_dpp v130, v138 row_shl:1 row_mask:0xf bank_mask:0xf
	v_cmp_gt_f32_e32 vcc, 0, v118
	v_mov_b32_dpp v131, v139 row_shl:1 row_mask:0xf bank_mask:0xf
	v_pk_fma_f32 v[124:125], v[54:55], v[130:131], v[124:125]
	v_pk_fma_f32 v[130:131], v[126:127], s[72:73], v[144:145] op_sel_hi:[1,0,0]
	v_pk_add_f32 v[124:125], v[58:59], v[124:125]
	v_pk_fma_f32 v[130:131], v[126:127], v[130:131], s[16:17] op_sel_hi:[1,1,0]
	s_nop 0
	v_pk_fma_f32 v[130:131], v[126:127], v[130:131], s[78:79] op_sel_hi:[1,1,0]
	s_nop 0
	v_pk_fma_f32 v[130:131], v[126:127], v[130:131], s[0:1] op_sel_hi:[1,1,0]
	s_nop 0
	v_pk_mul_f32 v[126:127], v[126:127], v[130:131]
	v_pk_mul_f32 v[130:131], v[118:119], v[118:119]
	s_nop 0
	v_pk_mul_f32 v[130:131], v[130:131], s[28:29] op_sel_hi:[1,0]
	s_nop 0
	v_exp_f32_e32 v130, v130
	v_exp_f32_e32 v131, v131
	s_nop 0
	v_pk_mul_f32 v[126:127], v[130:131], v[126:127]
	s_nop 0
	v_pk_mul_f32 v[130:131], v[118:119], v[126:127]
	v_pk_fma_f32 v[126:127], v[118:119], v[126:127], v[118:119] neg_lo:[1,0,0] neg_hi:[1,0,0]
	v_and_b32_e32 v118, 0x7fffffff, v124
	v_cndmask_b32_e32 v130, v126, v130, vcc
	v_cmp_gt_f32_e32 vcc, 0, v119
	v_and_b32_e32 v119, 0x7fffffff, v125
	v_pk_fma_f32 v[118:119], v[118:119], s[26:27], 1.0 op_sel_hi:[1,0,0]
	v_cndmask_b32_e32 v131, v127, v131, vcc
	v_rcp_f32_e32 v118, v118
	v_rcp_f32_e32 v119, v119
	v_cmp_gt_f32_e32 vcc, 0, v124
	v_pk_fma_f32 v[126:127], v[118:119], s[72:73], v[144:145] op_sel_hi:[1,0,0]
	s_nop 0
	v_pk_fma_f32 v[126:127], v[118:119], v[126:127], s[16:17] op_sel_hi:[1,1,0]
	s_nop 0
	v_pk_fma_f32 v[126:127], v[118:119], v[126:127], s[78:79] op_sel_hi:[1,1,0]
	s_nop 0
	v_pk_fma_f32 v[126:127], v[118:119], v[126:127], s[0:1] op_sel_hi:[1,1,0]
	s_nop 0
	v_pk_mul_f32 v[118:119], v[118:119], v[126:127]
	v_pk_mul_f32 v[126:127], v[124:125], v[124:125]
	s_nop 0
	v_pk_mul_f32 v[126:127], v[126:127], s[28:29] op_sel_hi:[1,0]
	s_nop 0
	v_exp_f32_e32 v126, v126
	v_exp_f32_e32 v127, v127
	s_nop 0
	v_pk_mul_f32 v[118:119], v[126:127], v[118:119]
	s_nop 0
	v_pk_mul_f32 v[126:127], v[124:125], v[118:119]
	v_pk_fma_f32 v[118:119], v[124:125], v[118:119], v[124:125] neg_lo:[1,0,0] neg_hi:[1,0,0]
	s_nop 0
	v_cndmask_b32_e32 v124, v118, v126, vcc
	v_cmp_gt_f32_e32 vcc, 0, v125
	v_mul_f32_e32 v118, v112, v130
	v_mul_f32_e32 v125, v113, v131
	v_cndmask_b32_e32 v119, v119, v127, vcc
	v_mul_f32_e32 v119, v115, v119
	v_cvt_pk_bf16_f32 v118, v118, v125
	v_mul_f32_e32 v124, v114, v124
	v_cvt_pk_bf16_f32 v119, v124, v119
	s_and_saveexec_b64 s[36:37], s[38:39]
	v_readlane_b32 s73, v255, 9
	s_cbranch_execz .LBB0_1555
	v_mov_b64_e32 v[124:125], s[56:57]
	v_mad_i64_i32 v[124:125], s[50:51], v160, s27, v[124:125]
	v_lshl_add_u64 v[124:125], v[188:189], 1, v[124:125]
	global_store_dwordx4 v[124:125], v[116:119], off

.LBB0_1557:
	s_or_b64 exec, exec, s[36:37]
	s_nop 1
	v_mov_b32_e32 v118, v228
	v_add_u32_e32 v119, 0x80, v190
	v_mov_b32_e32 v122, v209
	v_mov_b32_e32 v123, v209
	s_mov_b32 s10, 0xbf3a00e3
	s_nop 1
	v_pk_fma_f32 v[116:117], v[108:109], v[118:119], v[88:89] op_sel_hi:[1,0,1]
	s_nop 1
	v_mov_b32_e32 v108, v229
	v_pk_fma_f32 v[114:115], v[110:111], v[118:119], v[90:91] op_sel_hi:[1,0,1]
	v_pk_fma_f32 v[110:111], v[106:107], v[118:119], v[86:87] op_sel_hi:[1,0,1]
	v_mov_b32_dpp v122, v116 row_shr:1 row_mask:0xf bank_mask:0xf
	v_mov_b32_dpp v123, v117 row_shr:1 row_mask:0xf bank_mask:0xf
	v_pk_mul_f32 v[126:127], v[80:81], v[116:117]
	v_pk_fma_f32 v[112:113], v[104:105], v[118:119], v[84:85] op_sel_hi:[1,0,1]
	v_pk_fma_f32 v[122:123], v[68:69], v[122:123], v[126:127]
	v_mov_b32_e32 v126, v209
	v_mov_b32_e32 v127, v209
	v_pk_mul_f32 v[124:125], v[82:83], v[114:115]
	v_mov_b32_dpp v126, v114 row_shr:1 row_mask:0xf bank_mask:0xf
	v_mov_b32_dpp v127, v115 row_shr:1 row_mask:0xf bank_mask:0xf
	v_pk_fma_f32 v[124:125], v[70:71], v[126:127], v[124:125]
	v_pk_mul_f32 v[132:133], v[60:61], v[112:113]
	v_pk_fma_f32 v[42:43], v[42:43], v[118:119], v[46:47] op_sel_hi:[1,0,1]
	v_pk_fma_f32 v[40:41], v[40:41], v[118:119], v[44:45] op_sel_hi:[1,0,1]
	s_nop 1
	v_pk_fma_f32 v[106:107], v[100:101], v[108:109], v[88:89] op_sel_hi:[1,0,1]
	s_nop 1
	v_mov_b32_dpp v120, v106 row_ror:15 row_mask:0xf bank_mask:0xf bound_ctrl:1
	v_mov_b32_dpp v121, v107 row_ror:15 row_mask:0xf bank_mask:0xf bound_ctrl:1
	v_pk_fma_f32 v[104:105], v[102:103], v[108:109], v[90:91] op_sel_hi:[1,0,1]
	v_mov_b32_dpp v120, v116 row_shl:1 row_mask:0xf bank_mask:0xf
	v_mov_b32_dpp v121, v117 row_shl:1 row_mask:0xf bank_mask:0xf
	v_pk_fma_f32 v[120:121], v[72:73], v[120:121], v[122:123]
	v_mov_b32_dpp v122, v104 row_ror:15 row_mask:0xf bank_mask:0xf bound_ctrl:1
	v_mov_b32_dpp v123, v105 row_ror:15 row_mask:0xf bank_mask:0xf bound_ctrl:1
	v_pk_add_f32 v[120:121], v[76:77], v[120:121]
	v_mov_b32_dpp v122, v114 row_shl:1 row_mask:0xf bank_mask:0xf
	v_mov_b32_dpp v123, v115 row_shl:1 row_mask:0xf bank_mask:0xf
	v_pk_fma_f32 v[122:123], v[74:75], v[122:123], v[124:125]
	v_and_b32_e32 v125, 0x7fffffff, v121
	v_and_b32_e32 v124, 0x7fffffff, v120
	v_pk_fma_f32 v[124:125], v[124:125], s[26:27], 1.0 op_sel_hi:[1,0,0]
	v_pk_fma_f32 v[100:101], v[98:99], v[108:109], v[86:87] op_sel_hi:[1,0,1]
	v_pk_fma_f32 v[102:103], v[96:97], v[108:109], v[84:85] op_sel_hi:[1,0,1]
	s_nop 1
	v_mov_b32_e32 v98, v230
	s_nop 1
	v_mov_b32_e32 v96, v231
	v_rcp_f32_e32 v126, v124
	v_rcp_f32_e32 v127, v125
	v_mov_b64_e32 v[124:125], s[10:11]
	v_pk_add_f32 v[122:123], v[78:79], v[122:123]
	v_cmp_gt_f32_e32 vcc, 0, v120
	v_pk_fma_f32 v[130:131], v[126:127], s[72:73], v[124:125] op_sel_hi:[1,0,0]
	s_nop 0
	v_pk_fma_f32 v[130:131], v[126:127], v[130:131], s[16:17] op_sel_hi:[1,1,0]
	s_nop 0
	v_pk_fma_f32 v[130:131], v[126:127], v[130:131], s[78:79] op_sel_hi:[1,1,0]
	s_nop 0
	v_pk_fma_f32 v[130:131], v[126:127], v[130:131], s[0:1] op_sel_hi:[1,1,0]
	s_nop 0
	v_pk_mul_f32 v[126:127], v[126:127], v[130:131]
	v_pk_mul_f32 v[130:131], v[120:121], v[120:121]
	s_nop 0
	v_pk_mul_f32 v[130:131], v[130:131], s[28:29] op_sel_hi:[1,0]
	s_nop 0
	v_exp_f32_e32 v130, v130
	v_exp_f32_e32 v131, v131
	s_nop 0
	v_pk_mul_f32 v[126:127], v[130:131], v[126:127]
	s_nop 0
	v_pk_mul_f32 v[130:131], v[120:121], v[126:127]
	v_pk_fma_f32 v[126:127], v[120:121], v[126:127], v[120:121] neg_lo:[1,0,0] neg_hi:[1,0,0]
	v_and_b32_e32 v120, 0x7fffffff, v122
	v_cndmask_b32_e32 v97, v126, v130, vcc
	v_cmp_gt_f32_e32 vcc, 0, v121
	v_and_b32_e32 v121, 0x7fffffff, v123
	v_pk_fma_f32 v[120:121], v[120:121], s[26:27], 1.0 op_sel_hi:[1,0,0]
	v_cndmask_b32_e32 v99, v127, v131, vcc
	v_rcp_f32_e32 v120, v120
	v_rcp_f32_e32 v121, v121
	v_cmp_gt_f32_e32 vcc, 0, v122
	v_mov_b32_e32 v130, v209
	v_mov_b32_e32 v131, v209
	v_pk_fma_f32 v[126:127], v[120:121], s[72:73], v[124:125] op_sel_hi:[1,0,0]
	v_mov_b32_dpp v130, v112 row_shr:1 row_mask:0xf bank_mask:0xf
	v_pk_fma_f32 v[126:127], v[120:121], v[126:127], s[16:17] op_sel_hi:[1,1,0]
	v_mov_b32_dpp v131, v113 row_shr:1 row_mask:0xf bank_mask:0xf
	v_pk_fma_f32 v[126:127], v[120:121], v[126:127], s[78:79] op_sel_hi:[1,1,0]
	v_pk_fma_f32 v[130:131], v[48:49], v[130:131], v[132:133]
	v_pk_fma_f32 v[126:127], v[120:121], v[126:127], s[0:1] op_sel_hi:[1,1,0]
	v_mov_b32_e32 v132, v209
	v_pk_mul_f32 v[120:121], v[120:121], v[126:127]
	v_pk_mul_f32 v[126:127], v[122:123], v[122:123]
	v_mov_b32_e32 v133, v209
	v_pk_mul_f32 v[126:127], v[126:127], s[28:29] op_sel_hi:[1,0]
	v_mov_b32_dpp v132, v110 row_shr:1 row_mask:0xf bank_mask:0xf
	v_exp_f32_e32 v126, v126
	v_exp_f32_e32 v127, v127
	v_mov_b32_dpp v133, v111 row_shr:1 row_mask:0xf bank_mask:0xf
	v_pk_mul_f32 v[120:121], v[126:127], v[120:121]
	s_nop 0
	v_pk_mul_f32 v[126:127], v[122:123], v[120:121]
	v_pk_fma_f32 v[120:121], v[122:123], v[120:121], v[122:123] neg_lo:[1,0,0] neg_hi:[1,0,0]
	s_nop 0
	v_cndmask_b32_e32 v109, v120, v126, vcc
	v_cmp_gt_f32_e32 vcc, 0, v123
	v_pk_fma_f32 v[122:123], v[92:93], v[118:119], v[64:65] op_sel_hi:[1,0,1]
	s_nop 0
	v_cndmask_b32_e32 v126, v121, v127, vcc
	v_pk_fma_f32 v[120:121], v[94:95], v[118:119], v[66:67] op_sel_hi:[1,0,1]
	v_mul_f32_e32 v92, v122, v97
	v_mul_f32_e32 v93, v123, v99
	v_cvt_pk_bf16_f32 v92, v92, v93
	v_mul_f32_e32 v93, v120, v109
	v_mul_f32_e32 v94, v121, v126
	v_cvt_pk_bf16_f32 v93, v93, v94
	v_mov_b32_dpp v95, v103 row_ror:15 row_mask:0xf bank_mask:0xf bound_ctrl:1
	v_pk_mul_f32 v[126:127], v[62:63], v[110:111]
	v_mov_b32_dpp v94, v102 row_ror:15 row_mask:0xf bank_mask:0xf bound_ctrl:1
	v_mov_b32_dpp v95, v113 row_shl:1 row_mask:0xf bank_mask:0xf
	v_pk_fma_f32 v[126:127], v[50:51], v[132:133], v[126:127]
	v_mov_b32_dpp v94, v112 row_shl:1 row_mask:0xf bank_mask:0xf
	v_pk_fma_f32 v[94:95], v[52:53], v[94:95], v[130:131]
	v_mov_b32_dpp v130, v100 row_ror:15 row_mask:0xf bank_mask:0xf bound_ctrl:1
	v_mov_b32_dpp v131, v101 row_ror:15 row_mask:0xf bank_mask:0xf bound_ctrl:1
	v_pk_add_f32 v[94:95], v[56:57], v[94:95]
	v_mov_b32_dpp v130, v110 row_shl:1 row_mask:0xf bank_mask:0xf
	v_mov_b32_dpp v131, v111 row_shl:1 row_mask:0xf bank_mask:0xf
	v_pk_fma_f32 v[126:127], v[54:55], v[130:131], v[126:127]
	v_and_b32_e32 v131, 0x7fffffff, v95
	v_and_b32_e32 v130, 0x7fffffff, v94
	v_pk_fma_f32 v[130:131], v[130:131], s[26:27], 1.0 op_sel_hi:[1,0,0]
	v_pk_add_f32 v[126:127], v[58:59], v[126:127]
	v_rcp_f32_e32 v130, v130
	v_rcp_f32_e32 v131, v131
	v_cmp_gt_f32_e32 vcc, 0, v94
	v_pk_fma_f32 v[132:133], v[130:131], s[72:73], v[124:125] op_sel_hi:[1,0,0]
	s_nop 0
	v_pk_fma_f32 v[132:133], v[130:131], v[132:133], s[16:17] op_sel_hi:[1,1,0]
	s_nop 0
	v_pk_fma_f32 v[132:133], v[130:131], v[132:133], s[78:79] op_sel_hi:[1,1,0]
	s_nop 0
	v_pk_fma_f32 v[132:133], v[130:131], v[132:133], s[0:1] op_sel_hi:[1,1,0]
	s_nop 0
	v_pk_mul_f32 v[130:131], v[130:131], v[132:133]
	v_pk_mul_f32 v[132:133], v[94:95], v[94:95]
	s_nop 0
	v_pk_mul_f32 v[132:133], v[132:133], s[28:29] op_sel_hi:[1,0]
	s_nop 0
	v_exp_f32_e32 v132, v132
	v_exp_f32_e32 v133, v133
	s_nop 0
	v_pk_mul_f32 v[130:131], v[132:133], v[130:131]
	s_nop 0
	v_pk_mul_f32 v[132:133], v[94:95], v[130:131]
	v_pk_fma_f32 v[130:131], v[94:95], v[130:131], v[94:95] neg_lo:[1,0,0] neg_hi:[1,0,0]
	v_and_b32_e32 v94, 0x7fffffff, v126
	v_cndmask_b32_e32 v97, v130, v132, vcc
	v_cmp_gt_f32_e32 vcc, 0, v95
	v_and_b32_e32 v95, 0x7fffffff, v127
	v_pk_fma_f32 v[94:95], v[94:95], s[26:27], 1.0 op_sel_hi:[1,0,0]
	v_cndmask_b32_e32 v99, v131, v133, vcc
	v_rcp_f32_e32 v94, v94
	v_rcp_f32_e32 v95, v95
	v_cmp_gt_f32_e32 vcc, 0, v126
	v_pk_fma_f32 v[124:125], v[94:95], s[72:73], v[124:125] op_sel_hi:[1,0,0]
	s_nop 0
	v_pk_fma_f32 v[124:125], v[94:95], v[124:125], s[16:17] op_sel_hi:[1,1,0]
	s_nop 0
	v_pk_fma_f32 v[124:125], v[94:95], v[124:125], s[78:79] op_sel_hi:[1,1,0]
	s_nop 0
	v_pk_fma_f32 v[124:125], v[94:95], v[124:125], s[0:1] op_sel_hi:[1,1,0]
	s_nop 0
	v_pk_mul_f32 v[94:95], v[94:95], v[124:125]
	v_pk_mul_f32 v[124:125], v[126:127], v[126:127]
	s_nop 0
	v_pk_mul_f32 v[124:125], v[124:125], s[28:29] op_sel_hi:[1,0]
	s_nop 0
	v_exp_f32_e32 v124, v124
	v_exp_f32_e32 v125, v125
	s_nop 0
	v_pk_mul_f32 v[94:95], v[124:125], v[94:95]
	s_nop 0
	v_pk_mul_f32 v[124:125], v[126:127], v[94:95]
	v_pk_fma_f32 v[94:95], v[126:127], v[94:95], v[126:127] neg_lo:[1,0,0] neg_hi:[1,0,0]
	s_nop 0
	v_cndmask_b32_e32 v109, v94, v124, vcc
	v_cmp_gt_f32_e32 vcc, 0, v127
	v_mul_f32_e32 v94, v40, v97
	v_mul_f32_e32 v97, v41, v99
	v_cndmask_b32_e32 v95, v95, v125, vcc
	v_mul_f32_e32 v95, v43, v95
	v_cvt_pk_bf16_f32 v94, v94, v97
	v_mul_f32_e32 v97, v42, v109
	v_cvt_pk_bf16_f32 v95, v97, v95
	s_and_saveexec_b64 s[36:37], s[44:45]
	s_cbranch_execz .LBB0_1559
	v_mov_b64_e32 v[124:125], s[56:57]
	v_mad_i64_i32 v[124:125], s[50:51], v119, s27, v[124:125]
	v_lshl_add_u64 v[124:125], v[188:189], 1, v[124:125]
	global_store_dwordx4 v[124:125], v[92:95], off

.LBB0_1561:
	s_or_b64 exec, exec, s[36:37]
	s_nop 1
	v_pk_fma_f32 v[40:41], v[36:37], v[98:99], v[88:89] op_sel_hi:[1,0,1]
	v_pk_fma_f32 v[36:37], v[32:33], v[98:99], v[84:85] op_sel_hi:[1,0,1]
	v_mov_b32_dpp v32, v116 row_ror:1 row_mask:0xf bank_mask:0xf bound_ctrl:1
	v_mov_b32_dpp v33, v117 row_ror:1 row_mask:0xf bank_mask:0xf bound_ctrl:1
	s_nop 1
	v_pk_fma_f32 v[28:29], v[28:29], v[96:97], v[88:89] op_sel_hi:[1,0,1]
	v_pk_fma_f32 v[24:25], v[24:25], v[96:97], v[84:85] op_sel_hi:[1,0,1]
	v_mov_b32_dpp v84, v40 row_ror:15 row_mask:0xf bank_mask:0xf bound_ctrl:1
	v_mov_b32_dpp v32, v106 row_shr:1 row_mask:0xf bank_mask:0xf
	v_mov_b32_dpp v85, v41 row_ror:15 row_mask:0xf bank_mask:0xf bound_ctrl:1
	v_mov_b32_dpp v33, v107 row_shr:1 row_mask:0xf bank_mask:0xf
	v_pk_mul_f32 v[88:89], v[80:81], v[106:107]
	v_mov_b32_dpp v84, v106 row_shl:1 row_mask:0xf bank_mask:0xf
	v_mov_b32_dpp v85, v107 row_shl:1 row_mask:0xf bank_mask:0xf
	v_pk_fma_f32 v[32:33], v[68:69], v[32:33], v[88:89]
	v_pk_fma_f32 v[34:35], v[34:35], v[98:99], v[86:87] op_sel_hi:[1,0,1]
	v_pk_fma_f32 v[32:33], v[72:73], v[84:85], v[32:33]
	v_pk_fma_f32 v[26:27], v[26:27], v[96:97], v[86:87] op_sel_hi:[1,0,1]
	v_pk_add_f32 v[84:85], v[76:77], v[32:33]
	v_mov_b32_dpp v32, v114 row_ror:1 row_mask:0xf bank_mask:0xf bound_ctrl:1
	v_mov_b32_dpp v33, v115 row_ror:1 row_mask:0xf bank_mask:0xf bound_ctrl:1
	v_pk_mul_f32 v[86:87], v[82:83], v[104:105]
	v_mov_b32_dpp v32, v104 row_shr:1 row_mask:0xf bank_mask:0xf
	v_mov_b32_dpp v33, v105 row_shr:1 row_mask:0xf bank_mask:0xf
	v_pk_fma_f32 v[32:33], v[70:71], v[32:33], v[86:87]
	v_and_b32_e32 v87, 0x7fffffff, v85
	v_and_b32_e32 v86, 0x7fffffff, v84
	v_pk_fma_f32 v[38:39], v[38:39], v[98:99], v[90:91] op_sel_hi:[1,0,1]
	v_pk_fma_f32 v[86:87], v[86:87], s[26:27], 1.0 op_sel_hi:[1,0,0]
	s_mov_b32 s10, 0xbf3a00e3
	v_mov_b32_dpp v88, v38 row_ror:15 row_mask:0xf bank_mask:0xf bound_ctrl:1
	v_mov_b32_dpp v89, v39 row_ror:15 row_mask:0xf bank_mask:0xf bound_ctrl:1
	v_rcp_f32_e32 v86, v86
	v_rcp_f32_e32 v87, v87
	v_mov_b32_dpp v88, v104 row_shl:1 row_mask:0xf bank_mask:0xf
	v_mov_b32_dpp v89, v105 row_shl:1 row_mask:0xf bank_mask:0xf
	v_pk_fma_f32 v[32:33], v[74:75], v[88:89], v[32:33]
	v_pk_mul_f32 v[92:93], v[84:85], v[84:85]
	v_pk_add_f32 v[88:89], v[78:79], v[32:33]
	v_mov_b64_e32 v[32:33], s[10:11]
	v_pk_fma_f32 v[30:31], v[30:31], v[96:97], v[90:91] op_sel_hi:[1,0,1]
	v_pk_fma_f32 v[90:91], v[86:87], s[72:73], v[32:33] op_sel_hi:[1,0,0]
	v_pk_mul_f32 v[92:93], v[92:93], s[28:29] op_sel_hi:[1,0]
	v_pk_fma_f32 v[90:91], v[86:87], v[90:91], s[16:17] op_sel_hi:[1,1,0]
	v_exp_f32_e32 v92, v92
	v_exp_f32_e32 v93, v93
	v_pk_fma_f32 v[90:91], v[86:87], v[90:91], s[78:79] op_sel_hi:[1,1,0]
	v_cmp_gt_f32_e32 vcc, 0, v84
	v_pk_fma_f32 v[90:91], v[86:87], v[90:91], s[0:1] op_sel_hi:[1,1,0]
	v_mov_b32_e32 v109, v108
	v_pk_mul_f32 v[86:87], v[86:87], v[90:91]
	v_pk_fma_f32 v[20:21], v[20:21], v[108:109], v[64:65]
	v_pk_mul_f32 v[86:87], v[92:93], v[86:87]
	v_and_b32_e32 v93, 0x7fffffff, v89
	v_and_b32_e32 v92, 0x7fffffff, v88
	v_pk_fma_f32 v[92:93], v[92:93], s[26:27], 1.0 op_sel_hi:[1,0,0]
	v_pk_mul_f32 v[90:91], v[84:85], v[86:87]
	v_rcp_f32_e32 v92, v92
	v_rcp_f32_e32 v93, v93
	v_pk_fma_f32 v[86:87], v[84:85], v[86:87], v[84:85] neg_lo:[1,0,0] neg_hi:[1,0,0]
	v_pk_fma_f32 v[16:17], v[16:17], v[108:109], v[44:45]
	v_cndmask_b32_e32 v90, v86, v90, vcc
	v_cmp_gt_f32_e32 vcc, 0, v85
	v_pk_fma_f32 v[84:85], v[92:93], s[72:73], v[32:33] op_sel_hi:[1,0,0]
	v_mul_f32_e32 v20, v20, v90
	v_cndmask_b32_e32 v91, v87, v91, vcc
	v_pk_mul_f32 v[86:87], v[88:89], v[88:89]
	v_pk_fma_f32 v[84:85], v[92:93], v[84:85], s[16:17] op_sel_hi:[1,1,0]
	v_pk_mul_f32 v[86:87], v[86:87], s[28:29] op_sel_hi:[1,0]
	v_pk_fma_f32 v[84:85], v[92:93], v[84:85], s[78:79] op_sel_hi:[1,1,0]
	v_exp_f32_e32 v86, v86
	v_exp_f32_e32 v87, v87
	v_pk_fma_f32 v[84:85], v[92:93], v[84:85], s[0:1] op_sel_hi:[1,1,0]
	v_cmp_gt_f32_e32 vcc, 0, v88
	v_pk_mul_f32 v[84:85], v[92:93], v[84:85]
	v_mul_f32_e32 v21, v21, v91
	v_pk_mul_f32 v[84:85], v[86:87], v[84:85]
	v_cvt_pk_bf16_f32 v20, v20, v21
	v_pk_mul_f32 v[90:91], v[60:61], v[102:103]
	v_pk_mul_f32 v[86:87], v[88:89], v[84:85]
	v_pk_fma_f32 v[84:85], v[88:89], v[84:85], v[88:89] neg_lo:[1,0,0] neg_hi:[1,0,0]
	v_add_u32_e32 v94, 0x90, v190
	v_cndmask_b32_e32 v86, v84, v86, vcc
	v_cmp_gt_f32_e32 vcc, 0, v89
	v_mov_b32_e32 v84, v108
	v_pk_mul_f32 v[88:89], v[62:63], v[100:101]
	v_cndmask_b32_e32 v87, v85, v87, vcc
	v_mov_b32_e32 v85, v108
	v_pk_fma_f32 v[22:23], v[22:23], v[84:85], v[66:67]
	v_pk_fma_f32 v[18:19], v[18:19], v[84:85], v[46:47]
	v_mul_f32_e32 v21, v22, v86
	v_mul_f32_e32 v22, v23, v87
	v_cvt_pk_bf16_f32 v21, v21, v22
	v_mov_b32_dpp v23, v113 row_ror:1 row_mask:0xf bank_mask:0xf bound_ctrl:1
	v_mov_b32_dpp v86, v36 row_ror:15 row_mask:0xf bank_mask:0xf bound_ctrl:1
	v_mov_b32_dpp v22, v112 row_ror:1 row_mask:0xf bank_mask:0xf bound_ctrl:1
	v_mov_b32_dpp v87, v37 row_ror:15 row_mask:0xf bank_mask:0xf bound_ctrl:1
	v_mov_b32_dpp v23, v103 row_shr:1 row_mask:0xf bank_mask:0xf
	v_mov_b32_dpp v22, v102 row_shr:1 row_mask:0xf bank_mask:0xf
	v_mov_b32_dpp v86, v102 row_shl:1 row_mask:0xf bank_mask:0xf
	v_mov_b32_dpp v87, v103 row_shl:1 row_mask:0xf bank_mask:0xf
	v_pk_fma_f32 v[22:23], v[48:49], v[22:23], v[90:91]
	v_mov_b32_dpp v90, v34 row_ror:15 row_mask:0xf bank_mask:0xf bound_ctrl:1
	v_pk_fma_f32 v[22:23], v[52:53], v[86:87], v[22:23]
	v_mov_b32_dpp v86, v110 row_ror:1 row_mask:0xf bank_mask:0xf bound_ctrl:1
	v_pk_add_f32 v[22:23], v[56:57], v[22:23]
	v_mov_b32_dpp v87, v111 row_ror:1 row_mask:0xf bank_mask:0xf bound_ctrl:1
	v_and_b32_e32 v93, 0x7fffffff, v23
	v_and_b32_e32 v92, 0x7fffffff, v22
	v_pk_fma_f32 v[92:93], v[92:93], s[26:27], 1.0 op_sel_hi:[1,0,0]
	v_mov_b32_dpp v86, v100 row_shr:1 row_mask:0xf bank_mask:0xf
	v_rcp_f32_e32 v92, v92
	v_rcp_f32_e32 v93, v93
	v_mov_b32_dpp v91, v35 row_ror:15 row_mask:0xf bank_mask:0xf bound_ctrl:1
	v_mov_b32_dpp v87, v101 row_shr:1 row_mask:0xf bank_mask:0xf
	v_mov_b32_dpp v90, v100 row_shl:1 row_mask:0xf bank_mask:0xf
	v_mov_b32_dpp v91, v101 row_shl:1 row_mask:0xf bank_mask:0xf
	v_pk_fma_f32 v[86:87], v[50:51], v[86:87], v[88:89]
	v_pk_fma_f32 v[88:89], v[92:93], s[72:73], v[32:33] op_sel_hi:[1,0,0]
	v_pk_fma_f32 v[86:87], v[54:55], v[90:91], v[86:87]
	v_pk_mul_f32 v[90:91], v[22:23], v[22:23]
	v_pk_fma_f32 v[88:89], v[92:93], v[88:89], s[16:17] op_sel_hi:[1,1,0]
	v_pk_mul_f32 v[90:91], v[90:91], s[28:29] op_sel_hi:[1,0]
	v_pk_fma_f32 v[88:89], v[92:93], v[88:89], s[78:79] op_sel_hi:[1,1,0]
	v_exp_f32_e32 v90, v90
	v_exp_f32_e32 v91, v91
	v_pk_add_f32 v[86:87], v[58:59], v[86:87]
	v_pk_fma_f32 v[88:89], v[92:93], v[88:89], s[0:1] op_sel_hi:[1,1,0]
	v_cmp_gt_f32_e32 vcc, 0, v22
	v_pk_mul_f32 v[88:89], v[92:93], v[88:89]
	v_and_b32_e32 v93, 0x7fffffff, v87
	v_and_b32_e32 v92, 0x7fffffff, v86
	v_pk_fma_f32 v[92:93], v[92:93], s[26:27], 1.0 op_sel_hi:[1,0,0]
	v_pk_mul_f32 v[88:89], v[90:91], v[88:89]
	v_rcp_f32_e32 v92, v92
	v_rcp_f32_e32 v93, v93
	v_pk_mul_f32 v[90:91], v[22:23], v[88:89]
	v_pk_fma_f32 v[88:89], v[22:23], v[88:89], v[22:23] neg_lo:[1,0,0] neg_hi:[1,0,0]
	s_movk_i32 s10, 0x2c00
	v_cndmask_b32_e32 v90, v88, v90, vcc
	v_cmp_gt_f32_e32 vcc, 0, v23
	v_pk_fma_f32 v[22:23], v[92:93], s[72:73], v[32:33] op_sel_hi:[1,0,0]
	v_mul_f32_e32 v16, v16, v90
	v_cndmask_b32_e32 v91, v89, v91, vcc
	v_pk_mul_f32 v[88:89], v[86:87], v[86:87]
	v_pk_fma_f32 v[22:23], v[92:93], v[22:23], s[16:17] op_sel_hi:[1,1,0]
	v_pk_mul_f32 v[88:89], v[88:89], s[28:29] op_sel_hi:[1,0]
	v_pk_fma_f32 v[22:23], v[92:93], v[22:23], s[78:79] op_sel_hi:[1,1,0]
	v_exp_f32_e32 v88, v88
	v_exp_f32_e32 v89, v89
	v_pk_fma_f32 v[22:23], v[92:93], v[22:23], s[0:1] op_sel_hi:[1,1,0]
	v_cmp_gt_f32_e32 vcc, 0, v86
	v_pk_mul_f32 v[22:23], v[92:93], v[22:23]
	v_mul_f32_e32 v17, v17, v91
	v_pk_mul_f32 v[22:23], v[88:89], v[22:23]
	v_pk_mul_f32 v[84:85], v[80:81], v[40:41]
	v_pk_mul_f32 v[88:89], v[86:87], v[22:23]
	v_pk_fma_f32 v[22:23], v[86:87], v[22:23], v[86:87] neg_lo:[1,0,0] neg_hi:[1,0,0]
	v_pk_fma_f32 v[12:13], v[12:13], v[98:99], v[64:65] op_sel_hi:[1,0,1]
	v_cndmask_b32_e32 v86, v22, v88, vcc
	v_cmp_gt_f32_e32 vcc, 0, v87
	v_cvt_pk_bf16_f32 v22, v16, v17
	v_mul_f32_e32 v16, v18, v86
	v_pk_fma_f32 v[14:15], v[14:15], v[98:99], v[66:67] op_sel_hi:[1,0,1]
	v_cndmask_b32_e32 v23, v23, v89, vcc
	v_mul_f32_e32 v17, v19, v23
	v_cvt_pk_bf16_f32 v23, v16, v17
	v_mov_b64_e32 v[16:17], s[56:57]
	v_mad_i64_i32 v[18:19], s[36:37], v94, s10, v[16:17]
	v_lshl_add_u64 v[18:19], v[18:19], 0, v[128:129]
	global_store_dwordx4 v[18:19], v[20:23], off
	v_pk_fma_f32 v[8:9], v[8:9], v[98:99], v[44:45] op_sel_hi:[1,0,1]
	v_mov_b32_dpp v18, v106 row_ror:1 row_mask:0xf bank_mask:0xf bound_ctrl:1
	v_mov_b32_dpp v19, v107 row_ror:1 row_mask:0xf bank_mask:0xf bound_ctrl:1
	v_mov_b32_dpp v20, v28 row_ror:15 row_mask:0xf bank_mask:0xf bound_ctrl:1
	v_mov_b32_dpp v18, v40 row_shr:1 row_mask:0xf bank_mask:0xf
	v_mov_b32_dpp v21, v29 row_ror:15 row_mask:0xf bank_mask:0xf bound_ctrl:1
	v_mov_b32_dpp v19, v41 row_shr:1 row_mask:0xf bank_mask:0xf
	v_mov_b32_dpp v20, v40 row_shl:1 row_mask:0xf bank_mask:0xf
	v_mov_b32_dpp v21, v41 row_shl:1 row_mask:0xf bank_mask:0xf
	v_pk_fma_f32 v[18:19], v[68:69], v[18:19], v[84:85]
	v_pk_mul_f32 v[22:23], v[82:83], v[38:39]
	v_pk_fma_f32 v[18:19], v[72:73], v[20:21], v[18:19]
	v_mov_b32_dpp v20, v104 row_ror:1 row_mask:0xf bank_mask:0xf bound_ctrl:1
	v_pk_add_f32 v[18:19], v[76:77], v[18:19]
	v_mov_b32_dpp v21, v105 row_ror:1 row_mask:0xf bank_mask:0xf bound_ctrl:1
	v_and_b32_e32 v87, 0x7fffffff, v19
	v_and_b32_e32 v86, 0x7fffffff, v18
	v_pk_fma_f32 v[86:87], v[86:87], s[26:27], 1.0 op_sel_hi:[1,0,0]
	v_mov_b32_dpp v84, v30 row_ror:15 row_mask:0xf bank_mask:0xf bound_ctrl:1
	v_rcp_f32_e32 v86, v86
	v_rcp_f32_e32 v87, v87
	v_mov_b32_dpp v20, v38 row_shr:1 row_mask:0xf bank_mask:0xf
	v_mov_b32_dpp v85, v31 row_ror:15 row_mask:0xf bank_mask:0xf bound_ctrl:1
	v_mov_b32_dpp v21, v39 row_shr:1 row_mask:0xf bank_mask:0xf
	v_mov_b32_dpp v84, v38 row_shl:1 row_mask:0xf bank_mask:0xf
	v_mov_b32_dpp v85, v39 row_shl:1 row_mask:0xf bank_mask:0xf
	v_pk_fma_f32 v[20:21], v[70:71], v[20:21], v[22:23]
	v_pk_fma_f32 v[22:23], v[86:87], s[72:73], v[32:33] op_sel_hi:[1,0,0]
	v_pk_fma_f32 v[20:21], v[74:75], v[84:85], v[20:21]
	v_pk_mul_f32 v[84:85], v[18:19], v[18:19]
	v_pk_fma_f32 v[22:23], v[86:87], v[22:23], s[16:17] op_sel_hi:[1,1,0]
	v_pk_mul_f32 v[84:85], v[84:85], s[28:29] op_sel_hi:[1,0]
	v_pk_fma_f32 v[22:23], v[86:87], v[22:23], s[78:79] op_sel_hi:[1,1,0]
	v_exp_f32_e32 v84, v84
	v_exp_f32_e32 v85, v85
	v_pk_add_f32 v[20:21], v[78:79], v[20:21]
	v_pk_fma_f32 v[22:23], v[86:87], v[22:23], s[0:1] op_sel_hi:[1,1,0]
	v_cmp_gt_f32_e32 vcc, 0, v18
	v_pk_mul_f32 v[22:23], v[86:87], v[22:23]
	v_and_b32_e32 v87, 0x7fffffff, v21
	v_and_b32_e32 v86, 0x7fffffff, v20
	v_pk_fma_f32 v[86:87], v[86:87], s[26:27], 1.0 op_sel_hi:[1,0,0]
	v_pk_mul_f32 v[22:23], v[84:85], v[22:23]
	v_rcp_f32_e32 v86, v86
	v_rcp_f32_e32 v87, v87
	v_pk_mul_f32 v[84:85], v[18:19], v[22:23]
	v_pk_fma_f32 v[22:23], v[18:19], v[22:23], v[18:19] neg_lo:[1,0,0] neg_hi:[1,0,0]
	v_pk_fma_f32 v[10:11], v[10:11], v[98:99], v[46:47] op_sel_hi:[1,0,1]
	v_cndmask_b32_e32 v84, v22, v84, vcc
	v_cmp_gt_f32_e32 vcc, 0, v19
	v_pk_fma_f32 v[18:19], v[86:87], s[72:73], v[32:33] op_sel_hi:[1,0,0]
	v_mul_f32_e32 v12, v12, v84
	v_cndmask_b32_e32 v85, v23, v85, vcc
	v_pk_mul_f32 v[22:23], v[20:21], v[20:21]
	v_pk_fma_f32 v[18:19], v[86:87], v[18:19], s[16:17] op_sel_hi:[1,1,0]
	v_pk_mul_f32 v[22:23], v[22:23], s[28:29] op_sel_hi:[1,0]
	v_pk_fma_f32 v[18:19], v[86:87], v[18:19], s[78:79] op_sel_hi:[1,1,0]
	v_exp_f32_e32 v22, v22
	v_exp_f32_e32 v23, v23
	v_pk_fma_f32 v[18:19], v[86:87], v[18:19], s[0:1] op_sel_hi:[1,1,0]
	v_cmp_gt_f32_e32 vcc, 0, v20
	v_pk_mul_f32 v[18:19], v[86:87], v[18:19]
	v_mul_f32_e32 v13, v13, v85
	v_pk_mul_f32 v[18:19], v[22:23], v[18:19]
	v_cvt_pk_bf16_f32 v12, v12, v13
	v_add_u32_e32 v43, 0xa0, v190
	v_pk_mul_f32 v[22:23], v[20:21], v[18:19]
	v_pk_fma_f32 v[18:19], v[20:21], v[18:19], v[20:21] neg_lo:[1,0,0] neg_hi:[1,0,0]
	v_pk_fma_f32 v[2:3], v[2:3], v[96:97], v[46:47] op_sel_hi:[1,0,1]
	v_cndmask_b32_e32 v18, v18, v22, vcc
	v_cmp_gt_f32_e32 vcc, 0, v21
	v_mul_f32_e32 v13, v14, v18
	v_mov_b32_dpp v18, v24 row_ror:15 row_mask:0xf bank_mask:0xf bound_ctrl:1
	v_cndmask_b32_e32 v19, v19, v23, vcc
	v_mul_f32_e32 v14, v15, v19
	v_cvt_pk_bf16_f32 v13, v13, v14
	v_mov_b32_dpp v15, v103 row_ror:1 row_mask:0xf bank_mask:0xf bound_ctrl:1
	v_mov_b32_dpp v19, v25 row_ror:15 row_mask:0xf bank_mask:0xf bound_ctrl:1
	v_mov_b32_dpp v14, v102 row_ror:1 row_mask:0xf bank_mask:0xf bound_ctrl:1
	v_mov_b32_dpp v15, v37 row_shr:1 row_mask:0xf bank_mask:0xf
	v_pk_mul_f32 v[22:23], v[60:61], v[36:37]
	v_mov_b32_dpp v14, v36 row_shr:1 row_mask:0xf bank_mask:0xf
	v_mov_b32_dpp v18, v36 row_shl:1 row_mask:0xf bank_mask:0xf
	v_mov_b32_dpp v19, v37 row_shl:1 row_mask:0xf bank_mask:0xf
	v_pk_fma_f32 v[14:15], v[48:49], v[14:15], v[22:23]
	v_pk_mul_f32 v[20:21], v[62:63], v[34:35]
	v_pk_fma_f32 v[14:15], v[52:53], v[18:19], v[14:15]
	v_mov_b32_dpp v18, v100 row_ror:1 row_mask:0xf bank_mask:0xf bound_ctrl:1
	v_pk_add_f32 v[14:15], v[56:57], v[14:15]
	v_mov_b32_dpp v19, v101 row_ror:1 row_mask:0xf bank_mask:0xf bound_ctrl:1
	v_and_b32_e32 v85, 0x7fffffff, v15
	v_and_b32_e32 v84, 0x7fffffff, v14
	v_pk_fma_f32 v[84:85], v[84:85], s[26:27], 1.0 op_sel_hi:[1,0,0]
	v_mov_b32_dpp v22, v26 row_ror:15 row_mask:0xf bank_mask:0xf bound_ctrl:1
	v_rcp_f32_e32 v84, v84
	v_rcp_f32_e32 v85, v85
	v_mov_b32_dpp v18, v34 row_shr:1 row_mask:0xf bank_mask:0xf
	v_mov_b32_dpp v23, v27 row_ror:15 row_mask:0xf bank_mask:0xf bound_ctrl:1
	v_mov_b32_dpp v19, v35 row_shr:1 row_mask:0xf bank_mask:0xf
	v_mov_b32_dpp v22, v34 row_shl:1 row_mask:0xf bank_mask:0xf
	v_mov_b32_dpp v23, v35 row_shl:1 row_mask:0xf bank_mask:0xf
	v_pk_fma_f32 v[18:19], v[50:51], v[18:19], v[20:21]
	v_pk_fma_f32 v[20:21], v[84:85], s[72:73], v[32:33] op_sel_hi:[1,0,0]
	v_pk_fma_f32 v[18:19], v[54:55], v[22:23], v[18:19]
	v_pk_mul_f32 v[22:23], v[14:15], v[14:15]
	v_pk_fma_f32 v[20:21], v[84:85], v[20:21], s[16:17] op_sel_hi:[1,1,0]
	v_pk_mul_f32 v[22:23], v[22:23], s[28:29] op_sel_hi:[1,0]
	v_pk_fma_f32 v[20:21], v[84:85], v[20:21], s[78:79] op_sel_hi:[1,1,0]
	v_exp_f32_e32 v22, v22
	v_exp_f32_e32 v23, v23
	v_pk_add_f32 v[18:19], v[58:59], v[18:19]
	v_pk_fma_f32 v[20:21], v[84:85], v[20:21], s[0:1] op_sel_hi:[1,1,0]
	v_cmp_gt_f32_e32 vcc, 0, v14
	v_pk_mul_f32 v[20:21], v[84:85], v[20:21]
	v_and_b32_e32 v85, 0x7fffffff, v19
	v_and_b32_e32 v84, 0x7fffffff, v18
	v_pk_fma_f32 v[84:85], v[84:85], s[26:27], 1.0 op_sel_hi:[1,0,0]
	v_pk_mul_f32 v[20:21], v[22:23], v[20:21]
	v_rcp_f32_e32 v84, v84
	v_rcp_f32_e32 v85, v85
	v_pk_mul_f32 v[22:23], v[14:15], v[20:21]
	v_pk_fma_f32 v[20:21], v[14:15], v[20:21], v[14:15] neg_lo:[1,0,0] neg_hi:[1,0,0]
	v_pk_fma_f32 v[0:1], v[0:1], v[96:97], v[44:45] op_sel_hi:[1,0,1]
	v_cndmask_b32_e32 v22, v20, v22, vcc
	v_cmp_gt_f32_e32 vcc, 0, v15
	v_pk_fma_f32 v[14:15], v[84:85], s[72:73], v[32:33] op_sel_hi:[1,0,0]
	v_mul_f32_e32 v8, v8, v22
	v_cndmask_b32_e32 v23, v21, v23, vcc
	v_pk_mul_f32 v[20:21], v[18:19], v[18:19]
	v_pk_fma_f32 v[14:15], v[84:85], v[14:15], s[16:17] op_sel_hi:[1,1,0]
	v_pk_mul_f32 v[20:21], v[20:21], s[28:29] op_sel_hi:[1,0]
	v_pk_fma_f32 v[14:15], v[84:85], v[14:15], s[78:79] op_sel_hi:[1,1,0]
	v_exp_f32_e32 v20, v20
	v_exp_f32_e32 v21, v21
	v_pk_fma_f32 v[14:15], v[84:85], v[14:15], s[0:1] op_sel_hi:[1,1,0]
	v_cmp_gt_f32_e32 vcc, 0, v18
	v_pk_mul_f32 v[14:15], v[84:85], v[14:15]
	v_mul_f32_e32 v9, v9, v23
	v_pk_mul_f32 v[14:15], v[20:21], v[14:15]
	v_add_u32_e32 v42, 0xb0, v190
	v_pk_mul_f32 v[20:21], v[18:19], v[14:15]
	v_pk_fma_f32 v[14:15], v[18:19], v[14:15], v[18:19] neg_lo:[1,0,0] neg_hi:[1,0,0]
	s_nop 0
	v_cndmask_b32_e32 v18, v14, v20, vcc
	v_cmp_gt_f32_e32 vcc, 0, v19
	v_cvt_pk_bf16_f32 v14, v8, v9
	v_mul_f32_e32 v8, v10, v18
	v_mov_b32_e32 v10, v209
	v_cndmask_b32_e32 v15, v15, v21, vcc
	v_mul_f32_e32 v9, v11, v15
	v_cvt_pk_bf16_f32 v15, v8, v9
	v_mad_i64_i32 v[8:9], s[36:37], v43, s10, v[16:17]
	v_lshl_add_u64 v[8:9], v[8:9], 0, v[128:129]
	global_store_dwordx4 v[8:9], v[12:15], off
	v_mov_b32_e32 v11, v209
	v_mov_b32_dpp v8, v40 row_ror:1 row_mask:0xf bank_mask:0xf bound_ctrl:1
	v_mov_b32_dpp v9, v41 row_ror:1 row_mask:0xf bank_mask:0xf bound_ctrl:1
	v_pk_mul_f32 v[14:15], v[80:81], v[28:29]
	v_mov_b32_dpp v8, v28 row_shr:1 row_mask:0xf bank_mask:0xf
	v_mov_b32_dpp v9, v29 row_shr:1 row_mask:0xf bank_mask:0xf
	v_mov_b32_dpp v10, v28 row_shl:1 row_mask:0xf bank_mask:0xf
	v_mov_b32_dpp v11, v29 row_shl:1 row_mask:0xf bank_mask:0xf
	v_pk_fma_f32 v[8:9], v[68:69], v[8:9], v[14:15]
	v_pk_mul_f32 v[12:13], v[82:83], v[30:31]
	v_pk_fma_f32 v[8:9], v[72:73], v[10:11], v[8:9]
	v_mov_b32_dpp v10, v38 row_ror:1 row_mask:0xf bank_mask:0xf bound_ctrl:1
	v_pk_add_f32 v[8:9], v[76:77], v[8:9]
	v_mov_b32_dpp v11, v39 row_ror:1 row_mask:0xf bank_mask:0xf bound_ctrl:1
	v_and_b32_e32 v17, 0x7fffffff, v9
	v_and_b32_e32 v16, 0x7fffffff, v8
	v_pk_fma_f32 v[16:17], v[16:17], s[26:27], 1.0 op_sel_hi:[1,0,0]
	v_mov_b32_dpp v10, v30 row_shr:1 row_mask:0xf bank_mask:0xf
	v_rcp_f32_e32 v16, v16
	v_rcp_f32_e32 v17, v17
	v_mov_b32_e32 v14, v209
	v_mov_b32_dpp v11, v31 row_shr:1 row_mask:0xf bank_mask:0xf
	v_mov_b32_e32 v15, v209
	v_mov_b32_dpp v14, v30 row_shl:1 row_mask:0xf bank_mask:0xf
	v_pk_fma_f32 v[10:11], v[70:71], v[10:11], v[12:13]
	v_mov_b32_dpp v15, v31 row_shl:1 row_mask:0xf bank_mask:0xf
	v_pk_fma_f32 v[10:11], v[74:75], v[14:15], v[10:11]
	v_pk_fma_f32 v[12:13], v[16:17], s[72:73], v[32:33] op_sel_hi:[1,0,0]
	v_pk_mul_f32 v[14:15], v[8:9], v[8:9]
	v_pk_fma_f32 v[12:13], v[16:17], v[12:13], s[16:17] op_sel_hi:[1,1,0]
	v_pk_mul_f32 v[14:15], v[14:15], s[28:29] op_sel_hi:[1,0]
	v_pk_fma_f32 v[12:13], v[16:17], v[12:13], s[78:79] op_sel_hi:[1,1,0]
	v_exp_f32_e32 v14, v14
	v_exp_f32_e32 v15, v15
	v_pk_add_f32 v[10:11], v[78:79], v[10:11]
	v_pk_fma_f32 v[12:13], v[16:17], v[12:13], s[0:1] op_sel_hi:[1,1,0]
	v_cmp_gt_f32_e32 vcc, 0, v8
	v_pk_mul_f32 v[12:13], v[16:17], v[12:13]
	v_and_b32_e32 v17, 0x7fffffff, v11
	v_and_b32_e32 v16, 0x7fffffff, v10
	v_pk_fma_f32 v[16:17], v[16:17], s[26:27], 1.0 op_sel_hi:[1,0,0]
	v_pk_mul_f32 v[12:13], v[14:15], v[12:13]
	v_rcp_f32_e32 v16, v16
	v_rcp_f32_e32 v17, v17
	v_pk_mul_f32 v[14:15], v[8:9], v[12:13]
	v_pk_fma_f32 v[12:13], v[8:9], v[12:13], v[8:9] neg_lo:[1,0,0] neg_hi:[1,0,0]
	s_nop 0
	v_cndmask_b32_e32 v14, v12, v14, vcc
	v_cmp_gt_f32_e32 vcc, 0, v9
	v_pk_fma_f32 v[8:9], v[16:17], s[72:73], v[32:33] op_sel_hi:[1,0,0]
	s_nop 0
	v_cndmask_b32_e32 v15, v13, v15, vcc
	v_pk_mul_f32 v[12:13], v[10:11], v[10:11]
	v_pk_fma_f32 v[8:9], v[16:17], v[8:9], s[16:17] op_sel_hi:[1,1,0]
	v_pk_mul_f32 v[12:13], v[12:13], s[28:29] op_sel_hi:[1,0]
	v_pk_fma_f32 v[8:9], v[16:17], v[8:9], s[78:79] op_sel_hi:[1,1,0]
	v_exp_f32_e32 v12, v12
	v_exp_f32_e32 v13, v13
	v_pk_fma_f32 v[8:9], v[16:17], v[8:9], s[0:1] op_sel_hi:[1,1,0]
	v_cmp_gt_f32_e32 vcc, 0, v10
	v_pk_mul_f32 v[8:9], v[16:17], v[8:9]
	v_pk_mul_f32 v[16:17], v[60:61], v[24:25]
	v_pk_mul_f32 v[8:9], v[12:13], v[8:9]
	s_nop 0
	v_pk_mul_f32 v[12:13], v[10:11], v[8:9]
	v_pk_fma_f32 v[8:9], v[10:11], v[8:9], v[10:11] neg_lo:[1,0,0] neg_hi:[1,0,0]
	s_nop 0
	v_cndmask_b32_e32 v12, v8, v12, vcc
	v_cmp_gt_f32_e32 vcc, 0, v11
	v_pk_fma_f32 v[10:11], v[4:5], v[96:97], v[64:65] op_sel_hi:[1,0,1]
	s_nop 0
	v_cndmask_b32_e32 v13, v9, v13, vcc
	v_pk_fma_f32 v[8:9], v[6:7], v[96:97], v[66:67] op_sel_hi:[1,0,1]
	v_mul_f32_e32 v4, v10, v14
	v_mul_f32_e32 v5, v11, v15
	v_cvt_pk_bf16_f32 v4, v4, v5
	v_mul_f32_e32 v5, v8, v12
	v_mul_f32_e32 v6, v9, v13
	v_cvt_pk_bf16_f32 v5, v5, v6
	v_mov_b32_dpp v7, v37 row_ror:1 row_mask:0xf bank_mask:0xf bound_ctrl:1
	v_mov_b32_e32 v12, v209
	v_mov_b32_dpp v6, v36 row_ror:1 row_mask:0xf bank_mask:0xf bound_ctrl:1
	v_mov_b32_dpp v7, v25 row_shr:1 row_mask:0xf bank_mask:0xf
	v_mov_b32_e32 v13, v209
	v_mov_b32_dpp v6, v24 row_shr:1 row_mask:0xf bank_mask:0xf
	v_mov_b32_dpp v12, v24 row_shl:1 row_mask:0xf bank_mask:0xf
	v_mov_b32_dpp v13, v25 row_shl:1 row_mask:0xf bank_mask:0xf
	v_pk_fma_f32 v[6:7], v[48:49], v[6:7], v[16:17]
	v_pk_mul_f32 v[14:15], v[62:63], v[26:27]
	v_pk_fma_f32 v[6:7], v[52:53], v[12:13], v[6:7]
	v_mov_b32_dpp v12, v34 row_ror:1 row_mask:0xf bank_mask:0xf bound_ctrl:1
	v_pk_add_f32 v[6:7], v[56:57], v[6:7]
	v_mov_b32_dpp v13, v35 row_ror:1 row_mask:0xf bank_mask:0xf bound_ctrl:1
	v_and_b32_e32 v19, 0x7fffffff, v7
	v_and_b32_e32 v18, 0x7fffffff, v6
	v_pk_fma_f32 v[18:19], v[18:19], s[26:27], 1.0 op_sel_hi:[1,0,0]
	v_mov_b32_dpp v12, v26 row_shr:1 row_mask:0xf bank_mask:0xf
	v_rcp_f32_e32 v18, v18
	v_rcp_f32_e32 v19, v19
	v_mov_b32_e32 v16, v209
	v_mov_b32_dpp v13, v27 row_shr:1 row_mask:0xf bank_mask:0xf
	v_mov_b32_e32 v17, v209
	v_mov_b32_dpp v16, v26 row_shl:1 row_mask:0xf bank_mask:0xf
	v_pk_fma_f32 v[12:13], v[50:51], v[12:13], v[14:15]
	v_mov_b32_dpp v17, v27 row_shl:1 row_mask:0xf bank_mask:0xf
	v_pk_fma_f32 v[12:13], v[54:55], v[16:17], v[12:13]
	v_pk_fma_f32 v[14:15], v[18:19], s[72:73], v[32:33] op_sel_hi:[1,0,0]
	v_pk_mul_f32 v[16:17], v[6:7], v[6:7]
	v_pk_fma_f32 v[14:15], v[18:19], v[14:15], s[16:17] op_sel_hi:[1,1,0]
	v_pk_mul_f32 v[16:17], v[16:17], s[28:29] op_sel_hi:[1,0]
	v_pk_fma_f32 v[14:15], v[18:19], v[14:15], s[78:79] op_sel_hi:[1,1,0]
	v_exp_f32_e32 v16, v16
	v_exp_f32_e32 v17, v17
	v_pk_add_f32 v[12:13], v[58:59], v[12:13]
	v_pk_fma_f32 v[14:15], v[18:19], v[14:15], s[0:1] op_sel_hi:[1,1,0]
	v_cmp_gt_f32_e32 vcc, 0, v6
	v_pk_mul_f32 v[14:15], v[18:19], v[14:15]
	v_and_b32_e32 v19, 0x7fffffff, v13
	v_and_b32_e32 v18, 0x7fffffff, v12
	v_pk_fma_f32 v[18:19], v[18:19], s[26:27], 1.0 op_sel_hi:[1,0,0]
	v_pk_mul_f32 v[14:15], v[16:17], v[14:15]
	v_rcp_f32_e32 v18, v18
	v_rcp_f32_e32 v19, v19
	v_pk_mul_f32 v[16:17], v[6:7], v[14:15]
	v_pk_fma_f32 v[14:15], v[6:7], v[14:15], v[6:7] neg_lo:[1,0,0] neg_hi:[1,0,0]
	s_nop 0
	v_cndmask_b32_e32 v16, v14, v16, vcc
	v_cmp_gt_f32_e32 vcc, 0, v7
	v_pk_fma_f32 v[6:7], v[18:19], s[72:73], v[32:33] op_sel_hi:[1,0,0]
	s_nop 0
	v_cndmask_b32_e32 v17, v15, v17, vcc
	v_pk_mul_f32 v[14:15], v[12:13], v[12:13]
	v_pk_fma_f32 v[6:7], v[18:19], v[6:7], s[16:17] op_sel_hi:[1,1,0]
	v_pk_mul_f32 v[14:15], v[14:15], s[28:29] op_sel_hi:[1,0]
	v_pk_fma_f32 v[6:7], v[18:19], v[6:7], s[78:79] op_sel_hi:[1,1,0]
	v_exp_f32_e32 v14, v14
	v_exp_f32_e32 v15, v15
	v_pk_fma_f32 v[6:7], v[18:19], v[6:7], s[0:1] op_sel_hi:[1,1,0]
	v_cmp_gt_f32_e32 vcc, 0, v12
	v_pk_mul_f32 v[6:7], v[18:19], v[6:7]
	s_nop 0
	v_pk_mul_f32 v[6:7], v[14:15], v[6:7]
	s_nop 0
	v_pk_mul_f32 v[14:15], v[12:13], v[6:7]
	v_pk_fma_f32 v[6:7], v[12:13], v[6:7], v[12:13] neg_lo:[1,0,0] neg_hi:[1,0,0]
	s_nop 0
	v_cndmask_b32_e32 v12, v6, v14, vcc
	v_cmp_gt_f32_e32 vcc, 0, v13
	v_mul_f32_e32 v6, v0, v16
	v_mul_f32_e32 v13, v1, v17
	v_cndmask_b32_e32 v7, v7, v15, vcc
	v_mul_f32_e32 v7, v3, v7
	v_cvt_pk_bf16_f32 v6, v6, v13
	v_mul_f32_e32 v12, v2, v12
	v_cvt_pk_bf16_f32 v7, v12, v7
	s_and_saveexec_b64 s[36:37], s[38:39]
	s_cbranch_execnz .LBB0_1564
	s_or_b64 exec, exec, s[36:37]
	s_and_saveexec_b64 s[36:37], s[42:43]
	s_cbranch_execnz .LBB0_1565
